# compression-MLP GEMM epilogue: 128 serialized per-element bias loads replaced by 4 vector loads per tile
# baseline (speedup 1.0000x reference)
; __device__ __forceinline__ unsigned cvt_pk_bf16(float lo, float hi) { unsigned r; asm volatile("v_cvt_pk_bf16_f32 %0, %1, %2" : "=v"(r) : "v"(lo), "v"(hi)); return r; }
; __device__ __forceinline__ float fsigmoid(float x) { return __builtin_amdgcn_rcpf(1.0f + __builtin_amdgcn_exp2f(-1.4426950408889634f * x)); }
;     __device__ __forceinline__ void operator()(const f32x4 (&acc)[2][2][4][2], const Unit& u, int wr, int wc, int fr, int fq) const {
;     ...
;                     for (int n = 0; n < 2; ++n)
; #pragma unroll
;                         for (int e = 0; e < 4; ++e) {
;                             float x = acc[ai][bj][m][n][e] * rs;
;                             if (cbias) x += cbias[(u.pm >> 5) * 256 + (col0 - colt) + bj * HALF + n * 4 + e];
;                             if (act == 1) x = fsigmoid(x);
;                             else if (act == 2) { const float z = 1.5957691216057308f * (x + 0.044715f * x * x * x); x = x * fsigmoid(z); }
;                             h[n * 4 + e] = x;
;                         }
;                     u32x4 w; w.x = cvt_pk_bf16(h[0], h[1]); w.y = cvt_pk_bf16(h[2], h[3]); w.z = cvt_pk_bf16(h[4], h[5]); w.w = cvt_pk_bf16(h[6], h[7]);
;                     *(u32x4*)(rowp + bj * HALF) = w;
.LBB0_1725:
	s_lshl_b32 s8, s54, 3
	s_and_b32 s8, s8, 0xffffff00
	v_or_b32_e32 v142, s8, v146
	v_cndmask_b32_e64 v143, 0, 1, s[14:15]
	v_cmp_ne_u32_e64 s[8:9], 1, v143
	s_andn2_b64 vcc, exec, s[14:15]
	v_ashrrev_i32_e32 v143, 31, v142
	v_lshl_add_u64 v[220:221], v[142:143], 2, s[2:3]
	global_load_dwordx4 v[224:227], v[220:221], off
	global_load_dwordx4 v[228:231], v[220:221], off offset:16
	global_load_dwordx4 v[232:235], v[220:221], off offset:512
	global_load_dwordx4 v[236:239], v[220:221], off offset:528
	s_waitcnt vmcnt(0)
	s_cbranch_vccnz .LBB0_1727
	v_add_f32_e32 v124, v124, v224
.LBB0_1727:
	s_and_b64 vcc, exec, s[8:9]
	s_cbranch_vccnz .LBB0_1729
	v_add_f32_e32 v125, v125, v225
.LBB0_1729:
	s_and_b64 vcc, exec, s[8:9]
	s_cbranch_vccnz .LBB0_1731
	v_add_f32_e32 v126, v126, v226
.LBB0_1731:
	s_and_b64 vcc, exec, s[8:9]
	s_cbranch_vccnz .LBB0_1733
	v_add_f32_e32 v127, v127, v227
.LBB0_1733:
	s_and_b64 vcc, exec, s[8:9]
	s_cbranch_vccnz .LBB0_1735
	v_add_f32_e32 v120, v120, v228
.LBB0_1735:
	s_and_b64 vcc, exec, s[8:9]
	s_cbranch_vccnz .LBB0_1737
	v_add_f32_e32 v121, v121, v229
.LBB0_1737:
	s_and_b64 vcc, exec, s[8:9]
	s_cbranch_vccnz .LBB0_1739
	v_add_f32_e32 v122, v122, v230
.LBB0_1739:
	s_and_b64 vcc, exec, s[8:9]
	s_cbranch_vccnz .LBB0_1741
	v_add_f32_e32 v123, v123, v231
.LBB0_1741:
	v_mul_f32_e32 v150, 0x3d372713, v122
	v_mul_f32_e32 v150, v122, v150
	v_fma_f32 v150, v122, v150, v122
	v_mul_f32_e32 v150, 0x3fcc422a, v150
	v_mul_f32_e32 v150, 0xbfb8aa3b, v150
	v_exp_f32_e32 v150, v150
	v_mul_f32_e32 v151, 0x3d372713, v121
	v_mul_f32_e32 v151, v121, v151
	v_fma_f32 v151, v121, v151, v121
	v_mul_f32_e32 v151, 0x3fcc422a, v151
	v_add_f32_e32 v150, 1.0, v150
	v_mul_f32_e32 v151, 0xbfb8aa3b, v151
	v_rcp_f32_e32 v150, v150
	v_exp_f32_e32 v151, v151
	v_mul_f32_e32 v152, 0x3d372713, v127
	v_mul_f32_e32 v152, v127, v152
	v_mul_f32_e32 v150, v122, v150
	v_add_f32_e32 v122, 1.0, v151
	v_mul_f32_e32 v151, 0x3d372713, v120
	v_mul_f32_e32 v151, v120, v151
	v_fma_f32 v151, v120, v151, v120
	v_mul_f32_e32 v151, 0x3fcc422a, v151
	v_mul_f32_e32 v151, 0xbfb8aa3b, v151
	v_fma_f32 v152, v127, v152, v127
	v_exp_f32_e32 v151, v151
	v_mul_f32_e32 v152, 0x3fcc422a, v152
	v_mul_f32_e32 v153, 0x3d372713, v126
	v_mul_f32_e32 v152, 0xbfb8aa3b, v152
	v_mul_f32_e32 v153, v126, v153
	v_exp_f32_e32 v152, v152
	v_fma_f32 v153, v126, v153, v126
	v_mul_f32_e32 v153, 0x3fcc422a, v153
	v_add_f32_e32 v151, 1.0, v151
	v_mul_f32_e32 v153, 0xbfb8aa3b, v153
	v_rcp_f32_e32 v122, v122
	v_rcp_f32_e32 v151, v151
	v_exp_f32_e32 v153, v153
	v_add_f32_e32 v152, 1.0, v152
	v_rcp_f32_e32 v152, v152
	v_mul_f32_e32 v122, v121, v122
	v_mul_f32_e32 v151, v120, v151
	v_add_f32_e32 v120, 1.0, v153
	v_mul_f32_e32 v121, 0x3d372713, v125
	v_rcp_f32_e32 v120, v120
	v_mul_f32_e32 v121, v125, v121
	v_mul_f32_e32 v152, v127, v152
	v_fma_f32 v121, v125, v121, v125
	v_mul_f32_e32 v127, 0x3d372713, v124
	v_mul_f32_e32 v121, 0x3fcc422a, v121
	v_mul_f32_e32 v127, v124, v127
	v_mul_f32_e32 v121, 0xbfb8aa3b, v121
	v_fma_f32 v127, v124, v127, v124
	v_exp_f32_e32 v121, v121
	v_mul_f32_e32 v127, 0x3fcc422a, v127
	v_mul_f32_e32 v153, v126, v120
	v_mul_f32_e32 v126, 0x3d372713, v123
	v_mul_f32_e32 v127, 0xbfb8aa3b, v127
	v_mul_f32_e32 v126, v123, v126
	v_exp_f32_e32 v127, v127
	v_fma_f32 v126, v123, v126, v123
	v_mul_f32_e32 v126, 0x3fcc422a, v126
	v_add_f32_e32 v120, 1.0, v121
	v_mul_f32_e32 v126, 0xbfb8aa3b, v126
	v_rcp_f32_e32 v120, v120
	v_exp_f32_e32 v126, v126
	v_add_f32_e32 v121, 1.0, v127
	v_rcp_f32_e32 v121, v121
	v_mul_f32_e32 v154, v125, v120
	v_add_f32_e32 v120, 1.0, v126
	v_rcp_f32_e32 v156, v120
	v_mul_f32_e32 v155, v124, v121
	v_lshl_add_u32 v124, s54, 8, v144
	v_ashrrev_i32_e32 v125, 31, v124
	v_lshlrev_b64 v[120:121], 9, v[124:125]
	v_lshl_add_u64 v[126:127], v[136:137], 0, v[120:121]
	v_mul_f32_e32 v123, v123, v156
	v_cvt_pk_bf16_f32 v120, v155, v154
	v_cvt_pk_bf16_f32 v121, v153, v152
	v_cvt_pk_bf16_f32 v122, v151, v122
	v_cvt_pk_bf16_f32 v123, v150, v123
	global_store_dwordx4 v[126:127], v[120:123], off
	s_and_b64 vcc, exec, s[8:9]
	s_nop 0
	v_or_b32_e32 v120, 0x80, v142
	v_ashrrev_i32_e32 v121, 31, v120
	s_cbranch_vccnz .LBB0_1743
	v_add_f32_e32 v116, v116, v232
.LBB0_1743:
	s_and_b64 vcc, exec, s[8:9]
	s_cbranch_vccnz .LBB0_1745
	v_add_f32_e32 v117, v117, v233
.LBB0_1745:
	s_and_b64 vcc, exec, s[8:9]
	s_cbranch_vccnz .LBB0_1747
	v_add_f32_e32 v118, v118, v234
.LBB0_1747:
	s_and_b64 vcc, exec, s[8:9]
	s_cbranch_vccnz .LBB0_1749
	v_add_f32_e32 v119, v119, v235
.LBB0_1749:
	s_and_b64 vcc, exec, s[8:9]
	s_cbranch_vccnz .LBB0_1751
	v_add_f32_e32 v112, v112, v236
.LBB0_1751:
	s_and_b64 vcc, exec, s[8:9]
	s_cbranch_vccnz .LBB0_1753
	v_add_f32_e32 v113, v113, v237
.LBB0_1753:
	s_and_b64 vcc, exec, s[8:9]
	s_cbranch_vccnz .LBB0_1755
	v_add_f32_e32 v114, v114, v238
.LBB0_1755:
	s_and_b64 vcc, exec, s[8:9]
	s_cbranch_vccnz .LBB0_1757
	v_add_f32_e32 v115, v115, v239
; __device__ __forceinline__ unsigned cvt_pk_bf16(float lo, float hi) { unsigned r; asm volatile("v_cvt_pk_bf16_f32 %0, %1, %2" : "=v"(r) : "v"(lo), "v"(hi)); return r; }
; __device__ __forceinline__ float fsigmoid(float x) { return __builtin_amdgcn_rcpf(1.0f + __builtin_amdgcn_exp2f(-1.4426950408889634f * x)); }
;     __device__ __forceinline__ void operator()(const f32x4 (&acc)[2][2][4][2], const Unit& u, int wr, int wc, int fr, int fq) const {
;     ...
;                     for (int n = 0; n < 2; ++n)
; #pragma unroll
;                         for (int e = 0; e < 4; ++e) {
;                             float x = acc[ai][bj][m][n][e] * rs;
;                             if (cbias) x += cbias[(u.pm >> 5) * 256 + (col0 - colt) + bj * HALF + n * 4 + e];
;                             if (act == 1) x = fsigmoid(x);
;                             else if (act == 2) { const float z = 1.5957691216057308f * (x + 0.044715f * x * x * x); x = x * fsigmoid(z); }
;                             h[n * 4 + e] = x;
;                         }
;                     u32x4 w; w.x = cvt_pk_bf16(h[0], h[1]); w.y = cvt_pk_bf16(h[2], h[3]); w.z = cvt_pk_bf16(h[4], h[5]); w.w = cvt_pk_bf16(h[6], h[7]);
;                     *(u32x4*)(rowp + bj * HALF) = w;
.LBB0_1757:
	v_mul_f32_e32 v122, 0x3d372713, v114
	v_mul_f32_e32 v123, 0x3d372713, v113
	v_mul_f32_e32 v150, 0x3d372713, v112
	v_mul_f32_e32 v122, v114, v122
	v_mul_f32_e32 v123, v113, v123
	v_mul_f32_e32 v150, v112, v150
	v_fma_f32 v122, v114, v122, v114
	v_fma_f32 v123, v113, v123, v113
	v_fma_f32 v150, v112, v150, v112
	v_mul_f32_e32 v122, 0x3fcc422a, v122
	v_mul_f32_e32 v123, 0x3fcc422a, v123
	v_mul_f32_e32 v150, 0x3fcc422a, v150
	v_mul_f32_e32 v122, 0xbfb8aa3b, v122
	v_mul_f32_e32 v123, 0xbfb8aa3b, v123
	v_mul_f32_e32 v150, 0xbfb8aa3b, v150
	v_exp_f32_e32 v122, v122
	v_exp_f32_e32 v123, v123
	v_exp_f32_e32 v150, v150
	v_mul_f32_e32 v151, 0x3d372713, v119
	v_add_f32_e32 v122, 1.0, v122
	v_add_f32_e32 v123, 1.0, v123
	v_add_f32_e32 v150, 1.0, v150
	v_rcp_f32_e32 v122, v122
	v_rcp_f32_e32 v123, v123
	v_rcp_f32_e32 v150, v150
	v_mul_f32_e32 v151, v119, v151
	v_fma_f32 v151, v119, v151, v119
	v_mul_f32_e32 v151, 0x3fcc422a, v151
	v_mul_f32_e32 v151, 0xbfb8aa3b, v151
	v_exp_f32_e32 v151, v151
	v_mul_f32_e32 v122, v114, v122
	v_mul_f32_e32 v114, v113, v123
	v_mul_f32_e32 v123, v112, v150
	v_mul_f32_e32 v113, 0x3d372713, v118
	v_mul_f32_e32 v150, 0x3d372713, v117
	v_mul_f32_e32 v113, v118, v113
	v_mul_f32_e32 v150, v117, v150
	v_fma_f32 v113, v118, v113, v118
	v_fma_f32 v150, v117, v150, v117
	v_mul_f32_e32 v113, 0x3fcc422a, v113
	v_mul_f32_e32 v150, 0x3fcc422a, v150
	v_add_f32_e32 v112, 1.0, v151
	v_mul_f32_e32 v113, 0xbfb8aa3b, v113
	v_mul_f32_e32 v150, 0xbfb8aa3b, v150
	v_rcp_f32_e32 v112, v112
	v_exp_f32_e32 v113, v113
	v_exp_f32_e32 v150, v150
	v_mul_f32_e32 v151, 0x3d372713, v115
	v_mul_f32_e32 v119, v119, v112
	v_add_f32_e32 v112, 1.0, v113
	v_add_f32_e32 v113, 1.0, v150
	v_mul_f32_e32 v150, 0x3d372713, v116
	v_mul_f32_e32 v150, v116, v150
	v_mul_f32_e32 v151, v115, v151
	v_fma_f32 v150, v116, v150, v116
	v_fma_f32 v151, v115, v151, v115
	v_mul_f32_e32 v150, 0x3fcc422a, v150
	v_mul_f32_e32 v151, 0x3fcc422a, v151
	v_mul_f32_e32 v150, 0xbfb8aa3b, v150
	v_mul_f32_e32 v151, 0xbfb8aa3b, v151
	v_exp_f32_e32 v150, v150
	v_exp_f32_e32 v151, v151
	v_rcp_f32_e32 v112, v112
	v_rcp_f32_e32 v113, v113
	v_add_f32_e32 v150, 1.0, v150
	v_add_f32_e32 v151, 1.0, v151
	v_rcp_f32_e32 v150, v150
	v_rcp_f32_e32 v151, v151
	v_mul_f32_e32 v118, v118, v112
	v_mul_f32_e32 v112, v117, v113
	v_mul_f32_e32 v113, v116, v150
	v_mul_f32_e32 v115, v115, v151
	s_and_b64 vcc, exec, s[8:9]
	v_cvt_pk_bf16_f32 v112, v113, v112
	v_cvt_pk_bf16_f32 v113, v118, v119
	v_cvt_pk_bf16_f32 v114, v123, v114
	v_cvt_pk_bf16_f32 v115, v122, v115
	global_store_dwordx4 v[126:127], v[112:115], off offset:256
	s_cbranch_vccnz .LBB0_1759
	s_nop 0
	v_add_f32_e32 v108, v108, v224
.LBB0_1759:
	s_and_b64 vcc, exec, s[8:9]
	s_cbranch_vccnz .LBB0_1761
	v_add_f32_e32 v109, v109, v225
.LBB0_1761:
	s_and_b64 vcc, exec, s[8:9]
	s_cbranch_vccnz .LBB0_1763
	v_add_f32_e32 v110, v110, v226
.LBB0_1763:
	s_and_b64 vcc, exec, s[8:9]
	s_cbranch_vccnz .LBB0_1765
	v_add_f32_e32 v111, v111, v227
.LBB0_1765:
	s_and_b64 vcc, exec, s[8:9]
	s_cbranch_vccnz .LBB0_1767
	v_add_f32_e32 v104, v104, v228
.LBB0_1767:
	s_and_b64 vcc, exec, s[8:9]
	s_cbranch_vccnz .LBB0_1769
	v_add_f32_e32 v105, v105, v229
.LBB0_1769:
	s_and_b64 vcc, exec, s[8:9]
	s_cbranch_vccnz .LBB0_1771
	v_add_f32_e32 v106, v106, v230
.LBB0_1771:
	s_and_b64 vcc, exec, s[8:9]
	s_cbranch_vccnz .LBB0_1773
	v_add_f32_e32 v107, v107, v231
.LBB0_1773:
	v_mul_f32_e32 v112, 0x3d372713, v106
	v_mul_f32_e32 v112, v106, v112
	v_fma_f32 v112, v106, v112, v106
	v_mul_f32_e32 v112, 0x3fcc422a, v112
	v_mul_f32_e32 v112, 0xbfb8aa3b, v112
	v_exp_f32_e32 v112, v112
	v_mul_f32_e32 v113, 0x3d372713, v105
	v_mul_f32_e32 v113, v105, v113
	v_fma_f32 v113, v105, v113, v105
	v_mul_f32_e32 v113, 0x3fcc422a, v113
	v_add_f32_e32 v112, 1.0, v112
	v_mul_f32_e32 v113, 0xbfb8aa3b, v113
	v_rcp_f32_e32 v112, v112
	v_exp_f32_e32 v113, v113
	v_mul_f32_e32 v115, 0x3d372713, v110
	v_mul_f32_e32 v115, v110, v115
	v_mul_f32_e32 v112, v106, v112
	v_add_f32_e32 v106, 1.0, v113
	v_mul_f32_e32 v113, 0x3d372713, v104
	v_mul_f32_e32 v113, v104, v113
	v_fma_f32 v113, v104, v113, v104
	v_mul_f32_e32 v113, 0x3fcc422a, v113
	v_mul_f32_e32 v113, 0xbfb8aa3b, v113
	v_exp_f32_e32 v113, v113
	v_rcp_f32_e32 v106, v106
	v_fma_f32 v115, v110, v115, v110
	v_mul_f32_e32 v115, 0x3fcc422a, v115
	v_add_f32_e32 v113, 1.0, v113
	v_mul_f32_e32 v115, 0xbfb8aa3b, v115
	v_rcp_f32_e32 v113, v113
	v_exp_f32_e32 v115, v115
	v_mul_f32_e32 v116, v105, v106
	v_mul_f32_e32 v105, 0x3d372713, v109
	v_mul_f32_e32 v106, 0x3d372713, v108
	v_mul_f32_e32 v105, v109, v105
	v_mul_f32_e32 v106, v108, v106
	v_fma_f32 v105, v109, v105, v109
	v_fma_f32 v106, v108, v106, v108
	v_mul_f32_e32 v105, 0x3fcc422a, v105
	v_mul_f32_e32 v106, 0x3fcc422a, v106
	v_mul_f32_e32 v113, v104, v113
	v_add_f32_e32 v104, 1.0, v115
	v_mul_f32_e32 v105, 0xbfb8aa3b, v105
	v_mul_f32_e32 v106, 0xbfb8aa3b, v106
	v_rcp_f32_e32 v104, v104
	v_exp_f32_e32 v105, v105
	v_exp_f32_e32 v106, v106
	v_mul_f32_e32 v114, 0x3d372713, v111
	v_mul_f32_e32 v110, v110, v104
	v_add_f32_e32 v104, 1.0, v105
	v_add_f32_e32 v105, 1.0, v106
	v_mul_f32_e32 v106, 0x3d372713, v107
	v_mul_f32_e32 v114, v111, v114
	v_mul_f32_e32 v106, v107, v106
	v_fma_f32 v114, v111, v114, v111
	v_fma_f32 v106, v107, v106, v107
	v_mul_f32_e32 v114, 0x3fcc422a, v114
	v_mul_f32_e32 v106, 0x3fcc422a, v106
	v_mul_f32_e32 v114, 0xbfb8aa3b, v114
	v_mul_f32_e32 v106, 0xbfb8aa3b, v106
	v_exp_f32_e32 v114, v114
	v_rcp_f32_e32 v105, v105
	v_exp_f32_e32 v106, v106
	v_rcp_f32_e32 v104, v104
	v_add_f32_e32 v114, 1.0, v114
	v_mul_f32_e32 v108, v108, v105
	v_add_f32_e32 v105, 1.0, v106
	v_rcp_f32_e32 v114, v114
	v_mul_f32_e32 v109, v109, v104
	v_or_b32_e32 v104, 16, v124
	v_rcp_f32_e32 v106, v105
	v_ashrrev_i32_e32 v105, 31, v104
	v_lshlrev_b64 v[104:105], 9, v[104:105]
	v_lshl_add_u64 v[104:105], v[136:137], 0, v[104:105]
	s_and_b64 vcc, exec, s[8:9]
	v_mul_f32_e32 v111, v111, v114
	v_mul_f32_e32 v114, v107, v106
	v_cvt_pk_bf16_f32 v106, v108, v109
	v_cvt_pk_bf16_f32 v107, v110, v111
	v_cvt_pk_bf16_f32 v108, v113, v116
	v_cvt_pk_bf16_f32 v109, v112, v114
	global_store_dwordx4 v[104:105], v[106:109], off
	s_cbranch_vccnz .LBB0_1775
	s_nop 0
	v_add_f32_e32 v100, v100, v232
; __device__ __forceinline__ unsigned cvt_pk_bf16(float lo, float hi) { unsigned r; asm volatile("v_cvt_pk_bf16_f32 %0, %1, %2" : "=v"(r) : "v"(lo), "v"(hi)); return r; }
; __device__ __forceinline__ float fsigmoid(float x) { return __builtin_amdgcn_rcpf(1.0f + __builtin_amdgcn_exp2f(-1.4426950408889634f * x)); }
;     __device__ __forceinline__ void operator()(const f32x4 (&acc)[2][2][4][2], const Unit& u, int wr, int wc, int fr, int fq) const {
;     ...
;                     for (int n = 0; n < 2; ++n)
; #pragma unroll
;                         for (int e = 0; e < 4; ++e) {
;                             float x = acc[ai][bj][m][n][e] * rs;
;                             if (cbias) x += cbias[(u.pm >> 5) * 256 + (col0 - colt) + bj * HALF + n * 4 + e];
;                             if (act == 1) x = fsigmoid(x);
;                             else if (act == 2) { const float z = 1.5957691216057308f * (x + 0.044715f * x * x * x); x = x * fsigmoid(z); }
;                             h[n * 4 + e] = x;
;                         }
;                     u32x4 w; w.x = cvt_pk_bf16(h[0], h[1]); w.y = cvt_pk_bf16(h[2], h[3]); w.z = cvt_pk_bf16(h[4], h[5]); w.w = cvt_pk_bf16(h[6], h[7]);
;                     *(u32x4*)(rowp + bj * HALF) = w;
.LBB0_1775:
	s_and_b64 vcc, exec, s[8:9]
	s_cbranch_vccnz .LBB0_1777
	v_add_f32_e32 v101, v101, v233
.LBB0_1777:
	s_and_b64 vcc, exec, s[8:9]
	s_cbranch_vccnz .LBB0_1779
	v_add_f32_e32 v102, v102, v234
.LBB0_1779:
	s_and_b64 vcc, exec, s[8:9]
	s_cbranch_vccnz .LBB0_1781
	v_add_f32_e32 v103, v103, v235
.LBB0_1781:
	s_and_b64 vcc, exec, s[8:9]
	s_cbranch_vccnz .LBB0_1783
	v_add_f32_e32 v96, v96, v236
.LBB0_1783:
	s_and_b64 vcc, exec, s[8:9]
	s_cbranch_vccnz .LBB0_1785
	v_add_f32_e32 v97, v97, v237
.LBB0_1785:
	s_and_b64 vcc, exec, s[8:9]
	s_cbranch_vccnz .LBB0_1787
	v_add_f32_e32 v98, v98, v238
.LBB0_1787:
	s_and_b64 vcc, exec, s[8:9]
	s_cbranch_vccnz .LBB0_1789
	v_add_f32_e32 v99, v99, v239
.LBB0_1789:
	v_mul_f32_e32 v106, 0x3d372713, v98
	v_mul_f32_e32 v107, 0x3d372713, v97
	v_mul_f32_e32 v108, 0x3d372713, v96
	v_mul_f32_e32 v106, v98, v106
	v_mul_f32_e32 v107, v97, v107
	v_mul_f32_e32 v108, v96, v108
	v_fma_f32 v106, v98, v106, v98
	v_fma_f32 v107, v97, v107, v97
	v_fma_f32 v108, v96, v108, v96
	v_mul_f32_e32 v106, 0x3fcc422a, v106
	v_mul_f32_e32 v107, 0x3fcc422a, v107
	v_mul_f32_e32 v108, 0x3fcc422a, v108
	v_mul_f32_e32 v106, 0xbfb8aa3b, v106
	v_mul_f32_e32 v107, 0xbfb8aa3b, v107
	v_mul_f32_e32 v108, 0xbfb8aa3b, v108
	v_exp_f32_e32 v106, v106
	v_exp_f32_e32 v107, v107
	v_exp_f32_e32 v108, v108
	v_mul_f32_e32 v109, 0x3d372713, v103
	v_add_f32_e32 v106, 1.0, v106
	v_add_f32_e32 v107, 1.0, v107
	v_add_f32_e32 v108, 1.0, v108
	v_rcp_f32_e32 v106, v106
	v_rcp_f32_e32 v107, v107
	v_rcp_f32_e32 v108, v108
	v_mul_f32_e32 v109, v103, v109
	v_fma_f32 v109, v103, v109, v103
	v_mul_f32_e32 v109, 0x3fcc422a, v109
	v_mul_f32_e32 v109, 0xbfb8aa3b, v109
	v_exp_f32_e32 v109, v109
	v_mul_f32_e32 v106, v98, v106
	v_mul_f32_e32 v98, v97, v107
	v_mul_f32_e32 v107, v96, v108
	v_mul_f32_e32 v97, 0x3d372713, v102
	v_mul_f32_e32 v108, 0x3d372713, v101
	v_mul_f32_e32 v97, v102, v97
	v_mul_f32_e32 v108, v101, v108
	v_fma_f32 v97, v102, v97, v102
	v_fma_f32 v108, v101, v108, v101
	v_mul_f32_e32 v97, 0x3fcc422a, v97
	v_mul_f32_e32 v108, 0x3fcc422a, v108
	v_add_f32_e32 v96, 1.0, v109
	v_mul_f32_e32 v97, 0xbfb8aa3b, v97
	v_mul_f32_e32 v108, 0xbfb8aa3b, v108
	v_rcp_f32_e32 v96, v96
	v_exp_f32_e32 v97, v97
	v_exp_f32_e32 v108, v108
	v_mul_f32_e32 v109, 0x3d372713, v99
	v_mul_f32_e32 v103, v103, v96
	v_add_f32_e32 v96, 1.0, v97
	v_add_f32_e32 v97, 1.0, v108
	v_mul_f32_e32 v108, 0x3d372713, v100
	v_mul_f32_e32 v108, v100, v108
	v_mul_f32_e32 v109, v99, v109
	v_fma_f32 v108, v100, v108, v100
	v_fma_f32 v109, v99, v109, v99
	v_mul_f32_e32 v108, 0x3fcc422a, v108
	v_mul_f32_e32 v109, 0x3fcc422a, v109
	v_mul_f32_e32 v108, 0xbfb8aa3b, v108
	v_mul_f32_e32 v109, 0xbfb8aa3b, v109
	v_exp_f32_e32 v108, v108
	v_exp_f32_e32 v109, v109
	v_rcp_f32_e32 v96, v96
	v_rcp_f32_e32 v97, v97
	v_add_f32_e32 v108, 1.0, v108
	v_add_f32_e32 v109, 1.0, v109
	v_rcp_f32_e32 v108, v108
	v_rcp_f32_e32 v109, v109
	v_mul_f32_e32 v102, v102, v96
	v_mul_f32_e32 v96, v101, v97
	v_mul_f32_e32 v97, v100, v108
	v_mul_f32_e32 v99, v99, v109
	s_and_b64 vcc, exec, s[8:9]
	v_cvt_pk_bf16_f32 v96, v97, v96
	v_cvt_pk_bf16_f32 v97, v102, v103
	v_cvt_pk_bf16_f32 v98, v107, v98
	v_cvt_pk_bf16_f32 v99, v106, v99
	global_store_dwordx4 v[104:105], v[96:99], off offset:256
	s_cbranch_vccnz .LBB0_1791
	s_nop 0
	v_add_f32_e32 v92, v92, v224
.LBB0_1791:
	s_and_b64 vcc, exec, s[8:9]
	s_cbranch_vccnz .LBB0_1793
	v_add_f32_e32 v93, v93, v225
.LBB0_1793:
	s_and_b64 vcc, exec, s[8:9]
	s_cbranch_vccnz .LBB0_1795
	v_add_f32_e32 v94, v94, v226
.LBB0_1795:
	s_and_b64 vcc, exec, s[8:9]
	s_cbranch_vccnz .LBB0_1797
	v_add_f32_e32 v95, v95, v227
.LBB0_1797:
	s_and_b64 vcc, exec, s[8:9]
	s_cbranch_vccnz .LBB0_1799
	v_add_f32_e32 v88, v88, v228
.LBB0_1799:
	s_and_b64 vcc, exec, s[8:9]
	s_cbranch_vccnz .LBB0_1801
	v_add_f32_e32 v89, v89, v229
.LBB0_1801:
	s_and_b64 vcc, exec, s[8:9]
	s_cbranch_vccnz .LBB0_1803
	v_add_f32_e32 v90, v90, v230
.LBB0_1803:
	s_and_b64 vcc, exec, s[8:9]
	s_cbranch_vccnz .LBB0_1805
	v_add_f32_e32 v91, v91, v231
.LBB0_1805:
	v_mul_f32_e32 v96, 0x3d372713, v90
	v_mul_f32_e32 v96, v90, v96
	v_fma_f32 v96, v90, v96, v90
	v_mul_f32_e32 v96, 0x3fcc422a, v96
	v_mul_f32_e32 v96, 0xbfb8aa3b, v96
	v_exp_f32_e32 v96, v96
	v_mul_f32_e32 v97, 0x3d372713, v89
	v_mul_f32_e32 v97, v89, v97
	v_fma_f32 v97, v89, v97, v89
	v_mul_f32_e32 v97, 0x3fcc422a, v97
	v_add_f32_e32 v96, 1.0, v96
	v_mul_f32_e32 v97, 0xbfb8aa3b, v97
	v_rcp_f32_e32 v96, v96
	v_exp_f32_e32 v97, v97
	v_mul_f32_e32 v99, 0x3d372713, v94
	v_mul_f32_e32 v99, v94, v99
	v_mul_f32_e32 v96, v90, v96
	v_add_f32_e32 v90, 1.0, v97
	v_mul_f32_e32 v97, 0x3d372713, v88
	v_mul_f32_e32 v97, v88, v97
	v_fma_f32 v97, v88, v97, v88
	v_mul_f32_e32 v97, 0x3fcc422a, v97
	v_mul_f32_e32 v97, 0xbfb8aa3b, v97
	v_exp_f32_e32 v97, v97
	v_rcp_f32_e32 v90, v90
	v_fma_f32 v99, v94, v99, v94
	v_mul_f32_e32 v99, 0x3fcc422a, v99
	v_add_f32_e32 v97, 1.0, v97
	v_mul_f32_e32 v99, 0xbfb8aa3b, v99
	v_rcp_f32_e32 v97, v97
	v_exp_f32_e32 v99, v99
	v_mul_f32_e32 v100, v89, v90
	v_mul_f32_e32 v89, 0x3d372713, v93
	v_mul_f32_e32 v90, 0x3d372713, v92
	v_mul_f32_e32 v89, v93, v89
	v_mul_f32_e32 v90, v92, v90
	v_fma_f32 v89, v93, v89, v93
	v_fma_f32 v90, v92, v90, v92
	v_mul_f32_e32 v89, 0x3fcc422a, v89
	v_mul_f32_e32 v90, 0x3fcc422a, v90
	v_mul_f32_e32 v97, v88, v97
	v_add_f32_e32 v88, 1.0, v99
	v_mul_f32_e32 v89, 0xbfb8aa3b, v89
	v_mul_f32_e32 v90, 0xbfb8aa3b, v90
	v_rcp_f32_e32 v88, v88
	v_exp_f32_e32 v89, v89
	v_exp_f32_e32 v90, v90
	v_mul_f32_e32 v98, 0x3d372713, v95
	v_mul_f32_e32 v94, v94, v88
	v_add_f32_e32 v88, 1.0, v89
	v_add_f32_e32 v89, 1.0, v90
	v_mul_f32_e32 v90, 0x3d372713, v91
	v_mul_f32_e32 v98, v95, v98
	v_mul_f32_e32 v90, v91, v90
	v_fma_f32 v98, v95, v98, v95
	v_fma_f32 v90, v91, v90, v91
	v_mul_f32_e32 v98, 0x3fcc422a, v98
	v_mul_f32_e32 v90, 0x3fcc422a, v90
	v_mul_f32_e32 v98, 0xbfb8aa3b, v98
	v_mul_f32_e32 v90, 0xbfb8aa3b, v90
	v_exp_f32_e32 v98, v98
	v_rcp_f32_e32 v89, v89
	v_exp_f32_e32 v90, v90
	v_rcp_f32_e32 v88, v88
	v_add_f32_e32 v98, 1.0, v98
	v_mul_f32_e32 v92, v92, v89
	v_add_f32_e32 v89, 1.0, v90
	v_rcp_f32_e32 v98, v98
	v_mul_f32_e32 v93, v93, v88
	v_or_b32_e32 v88, 32, v124
	v_rcp_f32_e32 v90, v89
	v_ashrrev_i32_e32 v89, 31, v88
	v_lshlrev_b64 v[88:89], 9, v[88:89]
	v_lshl_add_u64 v[88:89], v[136:137], 0, v[88:89]
	s_and_b64 vcc, exec, s[8:9]
	v_mul_f32_e32 v95, v95, v98
	v_mul_f32_e32 v98, v91, v90
	v_cvt_pk_bf16_f32 v90, v92, v93
	v_cvt_pk_bf16_f32 v91, v94, v95
	v_cvt_pk_bf16_f32 v92, v97, v100
	v_cvt_pk_bf16_f32 v93, v96, v98
	global_store_dwordx4 v[88:89], v[90:93], off
	s_cbranch_vccnz .LBB0_1807
	s_nop 0
	v_add_f32_e32 v84, v84, v232
; __device__ __forceinline__ unsigned cvt_pk_bf16(float lo, float hi) { unsigned r; asm volatile("v_cvt_pk_bf16_f32 %0, %1, %2" : "=v"(r) : "v"(lo), "v"(hi)); return r; }
; __device__ __forceinline__ float fsigmoid(float x) { return __builtin_amdgcn_rcpf(1.0f + __builtin_amdgcn_exp2f(-1.4426950408889634f * x)); }
;     __device__ __forceinline__ void operator()(const f32x4 (&acc)[2][2][4][2], const Unit& u, int wr, int wc, int fr, int fq) const {
;     ...
;                     for (int n = 0; n < 2; ++n)
; #pragma unroll
;                         for (int e = 0; e < 4; ++e) {
;                             float x = acc[ai][bj][m][n][e] * rs;
;                             if (cbias) x += cbias[(u.pm >> 5) * 256 + (col0 - colt) + bj * HALF + n * 4 + e];
;                             if (act == 1) x = fsigmoid(x);
;                             else if (act == 2) { const float z = 1.5957691216057308f * (x + 0.044715f * x * x * x); x = x * fsigmoid(z); }
;                             h[n * 4 + e] = x;
;                         }
;                     u32x4 w; w.x = cvt_pk_bf16(h[0], h[1]); w.y = cvt_pk_bf16(h[2], h[3]); w.z = cvt_pk_bf16(h[4], h[5]); w.w = cvt_pk_bf16(h[6], h[7]);
;                     *(u32x4*)(rowp + bj * HALF) = w;
.LBB0_1807:
	s_and_b64 vcc, exec, s[8:9]
	s_cbranch_vccnz .LBB0_1809
	v_add_f32_e32 v85, v85, v233
.LBB0_1809:
	s_and_b64 vcc, exec, s[8:9]
	s_cbranch_vccnz .LBB0_1811
	v_add_f32_e32 v86, v86, v234
.LBB0_1811:
	s_and_b64 vcc, exec, s[8:9]
	s_cbranch_vccnz .LBB0_1813
	v_add_f32_e32 v87, v87, v235
.LBB0_1813:
	s_and_b64 vcc, exec, s[8:9]
	s_cbranch_vccnz .LBB0_1815
	v_add_f32_e32 v80, v80, v236
.LBB0_1815:
	s_and_b64 vcc, exec, s[8:9]
	s_cbranch_vccnz .LBB0_1817
	v_add_f32_e32 v81, v81, v237
.LBB0_1817:
	s_and_b64 vcc, exec, s[8:9]
	s_cbranch_vccnz .LBB0_1819
	v_add_f32_e32 v82, v82, v238
.LBB0_1819:
	s_and_b64 vcc, exec, s[8:9]
	s_cbranch_vccnz .LBB0_1821
	v_add_f32_e32 v83, v83, v239
.LBB0_1821:
	v_mul_f32_e32 v90, 0x3d372713, v82
	v_mul_f32_e32 v91, 0x3d372713, v81
	v_mul_f32_e32 v92, 0x3d372713, v80
	v_mul_f32_e32 v90, v82, v90
	v_mul_f32_e32 v91, v81, v91
	v_mul_f32_e32 v92, v80, v92
	v_fma_f32 v90, v82, v90, v82
	v_fma_f32 v91, v81, v91, v81
	v_fma_f32 v92, v80, v92, v80
	v_mul_f32_e32 v90, 0x3fcc422a, v90
	v_mul_f32_e32 v91, 0x3fcc422a, v91
	v_mul_f32_e32 v92, 0x3fcc422a, v92
	v_mul_f32_e32 v90, 0xbfb8aa3b, v90
	v_mul_f32_e32 v91, 0xbfb8aa3b, v91
	v_mul_f32_e32 v92, 0xbfb8aa3b, v92
	v_exp_f32_e32 v90, v90
	v_exp_f32_e32 v91, v91
	v_exp_f32_e32 v92, v92
	v_mul_f32_e32 v93, 0x3d372713, v87
	v_add_f32_e32 v90, 1.0, v90
	v_add_f32_e32 v91, 1.0, v91
	v_add_f32_e32 v92, 1.0, v92
	v_rcp_f32_e32 v90, v90
	v_rcp_f32_e32 v91, v91
	v_rcp_f32_e32 v92, v92
	v_mul_f32_e32 v93, v87, v93
	v_fma_f32 v93, v87, v93, v87
	v_mul_f32_e32 v93, 0x3fcc422a, v93
	v_mul_f32_e32 v93, 0xbfb8aa3b, v93
	v_exp_f32_e32 v93, v93
	v_mul_f32_e32 v90, v82, v90
	v_mul_f32_e32 v82, v81, v91
	v_mul_f32_e32 v91, v80, v92
	v_mul_f32_e32 v81, 0x3d372713, v86
	v_mul_f32_e32 v92, 0x3d372713, v85
	v_mul_f32_e32 v81, v86, v81
	v_mul_f32_e32 v92, v85, v92
	v_fma_f32 v81, v86, v81, v86
	v_fma_f32 v92, v85, v92, v85
	v_mul_f32_e32 v81, 0x3fcc422a, v81
	v_mul_f32_e32 v92, 0x3fcc422a, v92
	v_add_f32_e32 v80, 1.0, v93
	v_mul_f32_e32 v81, 0xbfb8aa3b, v81
	v_mul_f32_e32 v92, 0xbfb8aa3b, v92
	v_rcp_f32_e32 v80, v80
	v_exp_f32_e32 v81, v81
	v_exp_f32_e32 v92, v92
	v_mul_f32_e32 v93, 0x3d372713, v83
	v_mul_f32_e32 v87, v87, v80
	v_add_f32_e32 v80, 1.0, v81
	v_add_f32_e32 v81, 1.0, v92
	v_mul_f32_e32 v92, 0x3d372713, v84
	v_mul_f32_e32 v92, v84, v92
	v_mul_f32_e32 v93, v83, v93
	v_fma_f32 v92, v84, v92, v84
	v_fma_f32 v93, v83, v93, v83
	v_mul_f32_e32 v92, 0x3fcc422a, v92
	v_mul_f32_e32 v93, 0x3fcc422a, v93
	v_mul_f32_e32 v92, 0xbfb8aa3b, v92
	v_mul_f32_e32 v93, 0xbfb8aa3b, v93
	v_exp_f32_e32 v92, v92
	v_exp_f32_e32 v93, v93
	v_rcp_f32_e32 v80, v80
	v_rcp_f32_e32 v81, v81
	v_add_f32_e32 v92, 1.0, v92
	v_add_f32_e32 v93, 1.0, v93
	v_rcp_f32_e32 v92, v92
	v_rcp_f32_e32 v93, v93
	v_mul_f32_e32 v86, v86, v80
	v_mul_f32_e32 v80, v85, v81
	v_mul_f32_e32 v81, v84, v92
	v_mul_f32_e32 v83, v83, v93
	s_and_b64 vcc, exec, s[8:9]
	v_cvt_pk_bf16_f32 v80, v81, v80
	v_cvt_pk_bf16_f32 v81, v86, v87
	v_cvt_pk_bf16_f32 v82, v91, v82
	v_cvt_pk_bf16_f32 v83, v90, v83
	global_store_dwordx4 v[88:89], v[80:83], off offset:256
	s_cbranch_vccnz .LBB0_1823
	s_nop 0
	v_add_f32_e32 v76, v76, v224
.LBB0_1823:
	s_and_b64 vcc, exec, s[8:9]
	s_cbranch_vccnz .LBB0_1825
	v_add_f32_e32 v77, v77, v225
.LBB0_1825:
	s_and_b64 vcc, exec, s[8:9]
	s_cbranch_vccnz .LBB0_1827
	v_add_f32_e32 v78, v78, v226
.LBB0_1827:
	s_and_b64 vcc, exec, s[8:9]
	s_cbranch_vccnz .LBB0_1829
	v_add_f32_e32 v79, v79, v227
.LBB0_1829:
	s_and_b64 vcc, exec, s[8:9]
	s_cbranch_vccnz .LBB0_1831
	v_add_f32_e32 v72, v72, v228
.LBB0_1831:
	s_and_b64 vcc, exec, s[8:9]
	s_cbranch_vccnz .LBB0_1833
	v_add_f32_e32 v73, v73, v229
.LBB0_1833:
	s_and_b64 vcc, exec, s[8:9]
	s_cbranch_vccnz .LBB0_1835
	v_add_f32_e32 v74, v74, v230
.LBB0_1835:
	s_and_b64 vcc, exec, s[8:9]
	s_cbranch_vccnz .LBB0_1837
	v_add_f32_e32 v75, v75, v231
.LBB0_1837:
	v_mul_f32_e32 v80, 0x3d372713, v74
	v_mul_f32_e32 v80, v74, v80
	v_fma_f32 v80, v74, v80, v74
	v_mul_f32_e32 v80, 0x3fcc422a, v80
	v_mul_f32_e32 v80, 0xbfb8aa3b, v80
	v_exp_f32_e32 v80, v80
	v_mul_f32_e32 v81, 0x3d372713, v73
	v_mul_f32_e32 v81, v73, v81
	v_fma_f32 v81, v73, v81, v73
	v_mul_f32_e32 v81, 0x3fcc422a, v81
	v_add_f32_e32 v80, 1.0, v80
	v_mul_f32_e32 v81, 0xbfb8aa3b, v81
	v_rcp_f32_e32 v80, v80
	v_exp_f32_e32 v81, v81
	v_mul_f32_e32 v83, 0x3d372713, v78
	v_mul_f32_e32 v83, v78, v83
	v_mul_f32_e32 v80, v74, v80
	v_add_f32_e32 v74, 1.0, v81
	v_mul_f32_e32 v81, 0x3d372713, v72
	v_mul_f32_e32 v81, v72, v81
	v_fma_f32 v81, v72, v81, v72
	v_mul_f32_e32 v81, 0x3fcc422a, v81
	v_mul_f32_e32 v81, 0xbfb8aa3b, v81
	v_exp_f32_e32 v81, v81
	v_rcp_f32_e32 v74, v74
	v_fma_f32 v83, v78, v83, v78
	v_mul_f32_e32 v83, 0x3fcc422a, v83
	v_add_f32_e32 v81, 1.0, v81
	v_mul_f32_e32 v83, 0xbfb8aa3b, v83
	v_rcp_f32_e32 v81, v81
	v_exp_f32_e32 v83, v83
	v_mul_f32_e32 v84, v73, v74
	v_mul_f32_e32 v73, 0x3d372713, v77
	v_mul_f32_e32 v74, 0x3d372713, v76
	v_mul_f32_e32 v73, v77, v73
	v_mul_f32_e32 v74, v76, v74
	v_fma_f32 v73, v77, v73, v77
	v_fma_f32 v74, v76, v74, v76
	v_mul_f32_e32 v73, 0x3fcc422a, v73
	v_mul_f32_e32 v74, 0x3fcc422a, v74
	v_mul_f32_e32 v81, v72, v81
	v_add_f32_e32 v72, 1.0, v83
	v_mul_f32_e32 v73, 0xbfb8aa3b, v73
	v_mul_f32_e32 v74, 0xbfb8aa3b, v74
	v_rcp_f32_e32 v72, v72
	v_exp_f32_e32 v73, v73
	v_exp_f32_e32 v74, v74
	v_mul_f32_e32 v82, 0x3d372713, v79
	v_mul_f32_e32 v78, v78, v72
	v_add_f32_e32 v72, 1.0, v73
	v_add_f32_e32 v73, 1.0, v74
	v_mul_f32_e32 v74, 0x3d372713, v75
	v_mul_f32_e32 v82, v79, v82
	v_mul_f32_e32 v74, v75, v74
	v_fma_f32 v82, v79, v82, v79
	v_fma_f32 v74, v75, v74, v75
	v_mul_f32_e32 v82, 0x3fcc422a, v82
	v_mul_f32_e32 v74, 0x3fcc422a, v74
	v_mul_f32_e32 v82, 0xbfb8aa3b, v82
	v_mul_f32_e32 v74, 0xbfb8aa3b, v74
	v_exp_f32_e32 v82, v82
	v_rcp_f32_e32 v73, v73
	v_exp_f32_e32 v74, v74
	v_rcp_f32_e32 v72, v72
	v_add_f32_e32 v82, 1.0, v82
	v_mul_f32_e32 v76, v76, v73
	v_add_f32_e32 v73, 1.0, v74
	v_rcp_f32_e32 v82, v82
	v_mul_f32_e32 v77, v77, v72
	v_or_b32_e32 v72, 48, v124
	v_rcp_f32_e32 v74, v73
	v_ashrrev_i32_e32 v73, 31, v72
	v_lshlrev_b64 v[72:73], 9, v[72:73]
	v_lshl_add_u64 v[72:73], v[136:137], 0, v[72:73]
	s_and_b64 vcc, exec, s[8:9]
	v_mul_f32_e32 v79, v79, v82
	v_mul_f32_e32 v82, v75, v74
	v_cvt_pk_bf16_f32 v74, v76, v77
	v_cvt_pk_bf16_f32 v75, v78, v79
	v_cvt_pk_bf16_f32 v76, v81, v84
	v_cvt_pk_bf16_f32 v77, v80, v82
	global_store_dwordx4 v[72:73], v[74:77], off
	s_cbranch_vccnz .LBB0_1839
	s_nop 0
	v_add_f32_e32 v68, v68, v232
; __device__ __forceinline__ unsigned cvt_pk_bf16(float lo, float hi) { unsigned r; asm volatile("v_cvt_pk_bf16_f32 %0, %1, %2" : "=v"(r) : "v"(lo), "v"(hi)); return r; }
; __device__ __forceinline__ float fsigmoid(float x) { return __builtin_amdgcn_rcpf(1.0f + __builtin_amdgcn_exp2f(-1.4426950408889634f * x)); }
;     __device__ __forceinline__ void operator()(const f32x4 (&acc)[2][2][4][2], const Unit& u, int wr, int wc, int fr, int fq) const {
;     ...
;                     for (int n = 0; n < 2; ++n)
; #pragma unroll
;                         for (int e = 0; e < 4; ++e) {
;                             float x = acc[ai][bj][m][n][e] * rs;
;                             if (cbias) x += cbias[(u.pm >> 5) * 256 + (col0 - colt) + bj * HALF + n * 4 + e];
;                             if (act == 1) x = fsigmoid(x);
;                             else if (act == 2) { const float z = 1.5957691216057308f * (x + 0.044715f * x * x * x); x = x * fsigmoid(z); }
;                             h[n * 4 + e] = x;
;                         }
;                     u32x4 w; w.x = cvt_pk_bf16(h[0], h[1]); w.y = cvt_pk_bf16(h[2], h[3]); w.z = cvt_pk_bf16(h[4], h[5]); w.w = cvt_pk_bf16(h[6], h[7]);
;                     *(u32x4*)(rowp + bj * HALF) = w;
.LBB0_1839:
	s_and_b64 vcc, exec, s[8:9]
	s_cbranch_vccnz .LBB0_1841
	v_add_f32_e32 v69, v69, v233
.LBB0_1841:
	s_and_b64 vcc, exec, s[8:9]
	s_cbranch_vccnz .LBB0_1843
	v_add_f32_e32 v70, v70, v234
.LBB0_1843:
	s_and_b64 vcc, exec, s[8:9]
	s_cbranch_vccnz .LBB0_1845
	v_add_f32_e32 v71, v71, v235
.LBB0_1845:
	s_and_b64 vcc, exec, s[8:9]
	s_cbranch_vccnz .LBB0_1847
	v_add_f32_e32 v64, v64, v236
.LBB0_1847:
	s_and_b64 vcc, exec, s[8:9]
	s_cbranch_vccnz .LBB0_1849
	v_add_f32_e32 v65, v65, v237
.LBB0_1849:
	s_and_b64 vcc, exec, s[8:9]
	s_cbranch_vccnz .LBB0_1851
	v_add_f32_e32 v66, v66, v238
.LBB0_1851:
	s_and_b64 vcc, exec, s[8:9]
	s_cbranch_vccnz .LBB0_1853
	v_add_f32_e32 v67, v67, v239
.LBB0_1853:
	v_mul_f32_e32 v74, 0x3d372713, v66
	v_mul_f32_e32 v75, 0x3d372713, v65
	v_mul_f32_e32 v76, 0x3d372713, v64
	v_mul_f32_e32 v74, v66, v74
	v_mul_f32_e32 v75, v65, v75
	v_mul_f32_e32 v76, v64, v76
	v_fma_f32 v74, v66, v74, v66
	v_fma_f32 v75, v65, v75, v65
	v_fma_f32 v76, v64, v76, v64
	v_mul_f32_e32 v74, 0x3fcc422a, v74
	v_mul_f32_e32 v75, 0x3fcc422a, v75
	v_mul_f32_e32 v76, 0x3fcc422a, v76
	v_mul_f32_e32 v74, 0xbfb8aa3b, v74
	v_mul_f32_e32 v75, 0xbfb8aa3b, v75
	v_mul_f32_e32 v76, 0xbfb8aa3b, v76
	v_exp_f32_e32 v74, v74
	v_exp_f32_e32 v75, v75
	v_exp_f32_e32 v76, v76
	v_mul_f32_e32 v77, 0x3d372713, v71
	v_add_f32_e32 v74, 1.0, v74
	v_add_f32_e32 v75, 1.0, v75
	v_add_f32_e32 v76, 1.0, v76
	v_rcp_f32_e32 v74, v74
	v_rcp_f32_e32 v75, v75
	v_rcp_f32_e32 v76, v76
	v_mul_f32_e32 v77, v71, v77
	v_fma_f32 v77, v71, v77, v71
	v_mul_f32_e32 v77, 0x3fcc422a, v77
	v_mul_f32_e32 v77, 0xbfb8aa3b, v77
	v_exp_f32_e32 v77, v77
	v_mul_f32_e32 v74, v66, v74
	v_mul_f32_e32 v66, v65, v75
	v_mul_f32_e32 v75, v64, v76
	v_mul_f32_e32 v65, 0x3d372713, v70
	v_mul_f32_e32 v76, 0x3d372713, v69
	v_mul_f32_e32 v65, v70, v65
	v_mul_f32_e32 v76, v69, v76
	v_fma_f32 v65, v70, v65, v70
	v_fma_f32 v76, v69, v76, v69
	v_mul_f32_e32 v65, 0x3fcc422a, v65
	v_mul_f32_e32 v76, 0x3fcc422a, v76
	v_add_f32_e32 v64, 1.0, v77
	v_mul_f32_e32 v65, 0xbfb8aa3b, v65
	v_mul_f32_e32 v76, 0xbfb8aa3b, v76
	v_rcp_f32_e32 v64, v64
	v_exp_f32_e32 v65, v65
	v_exp_f32_e32 v76, v76
	v_mul_f32_e32 v77, 0x3d372713, v67
	v_mul_f32_e32 v71, v71, v64
	v_add_f32_e32 v64, 1.0, v65
	v_add_f32_e32 v65, 1.0, v76
	v_mul_f32_e32 v76, 0x3d372713, v68
	v_mul_f32_e32 v76, v68, v76
	v_mul_f32_e32 v77, v67, v77
	v_fma_f32 v76, v68, v76, v68
	v_fma_f32 v77, v67, v77, v67
	v_mul_f32_e32 v76, 0x3fcc422a, v76
	v_mul_f32_e32 v77, 0x3fcc422a, v77
	v_mul_f32_e32 v76, 0xbfb8aa3b, v76
	v_mul_f32_e32 v77, 0xbfb8aa3b, v77
	v_exp_f32_e32 v76, v76
	v_exp_f32_e32 v77, v77
	v_rcp_f32_e32 v64, v64
	v_rcp_f32_e32 v65, v65
	v_add_f32_e32 v76, 1.0, v76
	v_add_f32_e32 v77, 1.0, v77
	v_rcp_f32_e32 v76, v76
	v_rcp_f32_e32 v77, v77
	v_mul_f32_e32 v70, v70, v64
	v_mul_f32_e32 v64, v69, v65
	v_mul_f32_e32 v65, v68, v76
	v_mul_f32_e32 v67, v67, v77
	s_and_b64 vcc, exec, s[8:9]
	v_cvt_pk_bf16_f32 v64, v65, v64
	v_cvt_pk_bf16_f32 v65, v70, v71
	v_cvt_pk_bf16_f32 v66, v75, v66
	v_cvt_pk_bf16_f32 v67, v74, v67
	global_store_dwordx4 v[72:73], v[64:67], off offset:256
	s_cbranch_vccnz .LBB0_1855
	s_nop 0
	v_add_f32_e32 v60, v60, v224
.LBB0_1855:
	s_and_b64 vcc, exec, s[8:9]
	s_cbranch_vccnz .LBB0_1857
	v_add_f32_e32 v61, v61, v225
.LBB0_1857:
	s_and_b64 vcc, exec, s[8:9]
	s_cbranch_vccnz .LBB0_1859
	v_add_f32_e32 v62, v62, v226
.LBB0_1859:
	s_and_b64 vcc, exec, s[8:9]
	s_cbranch_vccnz .LBB0_1861
	v_add_f32_e32 v63, v63, v227
.LBB0_1861:
	s_and_b64 vcc, exec, s[8:9]
	s_cbranch_vccnz .LBB0_1863
	v_add_f32_e32 v56, v56, v228
.LBB0_1863:
	s_and_b64 vcc, exec, s[8:9]
	s_cbranch_vccnz .LBB0_1865
	v_add_f32_e32 v57, v57, v229
.LBB0_1865:
	s_and_b64 vcc, exec, s[8:9]
	s_cbranch_vccnz .LBB0_1867
	v_add_f32_e32 v58, v58, v230
.LBB0_1867:
	s_and_b64 vcc, exec, s[8:9]
	s_cbranch_vccnz .LBB0_1869
	v_add_f32_e32 v59, v59, v231
.LBB0_1869:
	v_mul_f32_e32 v64, 0x3d372713, v58
	v_mul_f32_e32 v64, v58, v64
	v_fma_f32 v64, v58, v64, v58
	v_mul_f32_e32 v64, 0x3fcc422a, v64
	v_mul_f32_e32 v64, 0xbfb8aa3b, v64
	v_exp_f32_e32 v64, v64
	v_mul_f32_e32 v65, 0x3d372713, v57
	v_mul_f32_e32 v65, v57, v65
	v_fma_f32 v65, v57, v65, v57
	v_add_f32_e32 v64, 1.0, v64
	v_mul_f32_e32 v65, 0x3fcc422a, v65
	v_rcp_f32_e32 v64, v64
	v_mul_f32_e32 v65, 0xbfb8aa3b, v65
	v_exp_f32_e32 v65, v65
	v_mul_f32_e32 v66, 0x3d372713, v56
	v_mul_f32_e32 v66, v56, v66
	v_fma_f32 v66, v56, v66, v56
	v_mul_f32_e32 v64, v58, v64
	v_mul_f32_e32 v58, 0x3d372713, v63
	v_mul_f32_e32 v66, 0x3fcc422a, v66
	v_mul_f32_e32 v58, v63, v58
	v_add_f32_e32 v65, 1.0, v65
	v_mul_f32_e32 v66, 0xbfb8aa3b, v66
	v_fma_f32 v58, v63, v58, v63
	v_rcp_f32_e32 v65, v65
	v_exp_f32_e32 v66, v66
	v_mul_f32_e32 v58, 0x3fcc422a, v58
	v_mul_f32_e32 v58, 0xbfb8aa3b, v58
	v_exp_f32_e32 v58, v58
	v_mul_f32_e32 v65, v57, v65
	v_add_f32_e32 v57, 1.0, v66
	v_rcp_f32_e32 v57, v57
	v_add_f32_e32 v58, 1.0, v58
	v_mul_f32_e32 v67, 0x3d372713, v61
	v_rcp_f32_e32 v58, v58
	v_mul_f32_e32 v67, v61, v67
	v_fma_f32 v67, v61, v67, v61
	v_mul_f32_e32 v67, 0x3fcc422a, v67
	v_mul_f32_e32 v68, v56, v57
	v_mul_f32_e32 v57, 0x3d372713, v60
	v_mul_f32_e32 v66, 0x3d372713, v62
	v_mul_f32_e32 v67, 0xbfb8aa3b, v67
	v_mul_f32_e32 v57, v60, v57
	v_mul_f32_e32 v66, v62, v66
	v_exp_f32_e32 v67, v67
	v_mul_f32_e32 v63, v63, v58
	v_fma_f32 v57, v60, v57, v60
	v_mul_f32_e32 v58, 0x3d372713, v59
	v_fma_f32 v66, v62, v66, v62
	v_mul_f32_e32 v57, 0x3fcc422a, v57
	v_mul_f32_e32 v58, v59, v58
	v_mul_f32_e32 v66, 0x3fcc422a, v66
	v_mul_f32_e32 v57, 0xbfb8aa3b, v57
	v_fma_f32 v58, v59, v58, v59
	v_mul_f32_e32 v66, 0xbfb8aa3b, v66
	v_exp_f32_e32 v57, v57
	v_mul_f32_e32 v58, 0x3fcc422a, v58
	v_exp_f32_e32 v66, v66
	v_add_f32_e32 v56, 1.0, v67
	v_mul_f32_e32 v58, 0xbfb8aa3b, v58
	v_rcp_f32_e32 v56, v56
	v_exp_f32_e32 v58, v58
	v_add_f32_e32 v57, 1.0, v57
	v_add_f32_e32 v66, 1.0, v66
	v_rcp_f32_e32 v57, v57
	v_rcp_f32_e32 v66, v66
	v_mul_f32_e32 v61, v61, v56
	v_add_f32_e32 v56, 1.0, v58
	v_rcp_f32_e32 v58, v56
	v_mul_f32_e32 v60, v60, v57
	v_lshlrev_b64 v[56:57], 9, v[124:125]
	v_mul_f32_e32 v62, v62, v66
	v_lshl_add_u64 v[56:57], v[136:137], 0, v[56:57]
	v_mul_f32_e32 v66, v59, v58
	v_cvt_pk_bf16_f32 v58, v60, v61
	v_cvt_pk_bf16_f32 v59, v62, v63
	v_add_co_u32_e32 v62, vcc, 0x10000, v56
	v_cvt_pk_bf16_f32 v60, v68, v65
	v_cvt_pk_bf16_f32 v61, v64, v66
	s_nop 1
	v_addc_co_u32_e32 v63, vcc, 0, v57, vcc
	s_and_b64 vcc, exec, s[8:9]
	global_store_dwordx4 v[62:63], v[58:61], off
	s_cbranch_vccnz .LBB0_1871
	s_nop 0
	v_add_f32_e32 v52, v52, v232
; __device__ __forceinline__ unsigned cvt_pk_bf16(float lo, float hi) { unsigned r; asm volatile("v_cvt_pk_bf16_f32 %0, %1, %2" : "=v"(r) : "v"(lo), "v"(hi)); return r; }
; __device__ __forceinline__ float fsigmoid(float x) { return __builtin_amdgcn_rcpf(1.0f + __builtin_amdgcn_exp2f(-1.4426950408889634f * x)); }
;     __device__ __forceinline__ void operator()(const f32x4 (&acc)[2][2][4][2], const Unit& u, int wr, int wc, int fr, int fq) const {
;     ...
;                     for (int n = 0; n < 2; ++n)
; #pragma unroll
;                         for (int e = 0; e < 4; ++e) {
;                             float x = acc[ai][bj][m][n][e] * rs;
;                             if (cbias) x += cbias[(u.pm >> 5) * 256 + (col0 - colt) + bj * HALF + n * 4 + e];
;                             if (act == 1) x = fsigmoid(x);
;                             else if (act == 2) { const float z = 1.5957691216057308f * (x + 0.044715f * x * x * x); x = x * fsigmoid(z); }
;                             h[n * 4 + e] = x;
;                         }
;                     u32x4 w; w.x = cvt_pk_bf16(h[0], h[1]); w.y = cvt_pk_bf16(h[2], h[3]); w.z = cvt_pk_bf16(h[4], h[5]); w.w = cvt_pk_bf16(h[6], h[7]);
;                     *(u32x4*)(rowp + bj * HALF) = w;
.LBB0_1871:
	s_and_b64 vcc, exec, s[8:9]
	s_cbranch_vccnz .LBB0_1873
	v_add_f32_e32 v53, v53, v233
.LBB0_1873:
	s_and_b64 vcc, exec, s[8:9]
	s_cbranch_vccnz .LBB0_1875
	v_add_f32_e32 v54, v54, v234
.LBB0_1875:
	s_and_b64 vcc, exec, s[8:9]
	s_cbranch_vccnz .LBB0_1877
	v_add_f32_e32 v55, v55, v235
.LBB0_1877:
	s_and_b64 vcc, exec, s[8:9]
	s_cbranch_vccnz .LBB0_1879
	v_add_f32_e32 v48, v48, v236
.LBB0_1879:
	s_and_b64 vcc, exec, s[8:9]
	s_cbranch_vccnz .LBB0_1881
	v_add_f32_e32 v49, v49, v237
.LBB0_1881:
	s_and_b64 vcc, exec, s[8:9]
	s_cbranch_vccnz .LBB0_1883
	v_add_f32_e32 v50, v50, v238
.LBB0_1883:
	s_and_b64 vcc, exec, s[8:9]
	s_cbranch_vccnz .LBB0_1885
	v_add_f32_e32 v51, v51, v239
.LBB0_1885:
	v_mul_f32_e32 v58, 0x3d372713, v50
	v_mul_f32_e32 v59, 0x3d372713, v49
	v_mul_f32_e32 v60, 0x3d372713, v48
	v_mul_f32_e32 v58, v50, v58
	v_mul_f32_e32 v59, v49, v59
	v_mul_f32_e32 v60, v48, v60
	v_fma_f32 v58, v50, v58, v50
	v_fma_f32 v59, v49, v59, v49
	v_fma_f32 v60, v48, v60, v48
	v_mul_f32_e32 v58, 0x3fcc422a, v58
	v_mul_f32_e32 v59, 0x3fcc422a, v59
	v_mul_f32_e32 v60, 0x3fcc422a, v60
	v_mul_f32_e32 v58, 0xbfb8aa3b, v58
	v_mul_f32_e32 v59, 0xbfb8aa3b, v59
	v_mul_f32_e32 v60, 0xbfb8aa3b, v60
	v_exp_f32_e32 v58, v58
	v_exp_f32_e32 v59, v59
	v_exp_f32_e32 v60, v60
	v_mul_f32_e32 v61, 0x3d372713, v55
	v_add_f32_e32 v58, 1.0, v58
	v_add_f32_e32 v59, 1.0, v59
	v_add_f32_e32 v60, 1.0, v60
	v_rcp_f32_e32 v58, v58
	v_rcp_f32_e32 v59, v59
	v_rcp_f32_e32 v60, v60
	v_mul_f32_e32 v61, v55, v61
	v_fma_f32 v61, v55, v61, v55
	v_mul_f32_e32 v61, 0x3fcc422a, v61
	v_mul_f32_e32 v61, 0xbfb8aa3b, v61
	v_exp_f32_e32 v61, v61
	v_mul_f32_e32 v58, v50, v58
	v_mul_f32_e32 v50, v49, v59
	v_mul_f32_e32 v59, v48, v60
	v_mul_f32_e32 v49, 0x3d372713, v54
	v_mul_f32_e32 v60, 0x3d372713, v53
	v_mul_f32_e32 v49, v54, v49
	v_mul_f32_e32 v60, v53, v60
	v_fma_f32 v49, v54, v49, v54
	v_fma_f32 v60, v53, v60, v53
	v_mul_f32_e32 v49, 0x3fcc422a, v49
	v_mul_f32_e32 v60, 0x3fcc422a, v60
	v_add_f32_e32 v48, 1.0, v61
	v_mul_f32_e32 v49, 0xbfb8aa3b, v49
	v_mul_f32_e32 v60, 0xbfb8aa3b, v60
	v_rcp_f32_e32 v48, v48
	v_exp_f32_e32 v49, v49
	v_exp_f32_e32 v60, v60
	v_mul_f32_e32 v61, 0x3d372713, v51
	v_mul_f32_e32 v55, v55, v48
	v_add_f32_e32 v48, 1.0, v49
	v_add_f32_e32 v49, 1.0, v60
	v_mul_f32_e32 v60, 0x3d372713, v52
	v_mul_f32_e32 v60, v52, v60
	v_mul_f32_e32 v61, v51, v61
	v_fma_f32 v60, v52, v60, v52
	v_fma_f32 v61, v51, v61, v51
	v_mul_f32_e32 v60, 0x3fcc422a, v60
	v_mul_f32_e32 v61, 0x3fcc422a, v61
	v_mul_f32_e32 v60, 0xbfb8aa3b, v60
	v_mul_f32_e32 v61, 0xbfb8aa3b, v61
	v_exp_f32_e32 v60, v60
	v_exp_f32_e32 v61, v61
	v_rcp_f32_e32 v48, v48
	v_rcp_f32_e32 v49, v49
	v_add_f32_e32 v60, 1.0, v60
	v_add_f32_e32 v61, 1.0, v61
	v_rcp_f32_e32 v60, v60
	v_rcp_f32_e32 v61, v61
	s_mov_b64 s[36:37], 0x10000
	v_lshl_add_u64 v[56:57], v[56:57], 0, s[36:37]
	v_mul_f32_e32 v54, v54, v48
	v_mul_f32_e32 v48, v53, v49
	v_mul_f32_e32 v49, v52, v60
	v_mul_f32_e32 v51, v51, v61
	s_and_b64 vcc, exec, s[8:9]
	v_cvt_pk_bf16_f32 v48, v49, v48
	v_cvt_pk_bf16_f32 v49, v54, v55
	v_cvt_pk_bf16_f32 v50, v59, v50
	v_cvt_pk_bf16_f32 v51, v58, v51
	global_store_dwordx4 v[56:57], v[48:51], off offset:256
	s_cbranch_vccnz .LBB0_1887
	s_nop 0
	v_add_f32_e32 v44, v44, v224
.LBB0_1887:
	s_and_b64 vcc, exec, s[8:9]
	s_cbranch_vccnz .LBB0_1889
	v_add_f32_e32 v45, v45, v225
.LBB0_1889:
	s_and_b64 vcc, exec, s[8:9]
	s_cbranch_vccnz .LBB0_1891
	v_add_f32_e32 v46, v46, v226
.LBB0_1891:
	s_and_b64 vcc, exec, s[8:9]
	s_cbranch_vccnz .LBB0_1893
	v_add_f32_e32 v47, v47, v227
.LBB0_1893:
	s_and_b64 vcc, exec, s[8:9]
	s_cbranch_vccnz .LBB0_1895
	v_add_f32_e32 v40, v40, v228
.LBB0_1895:
	s_and_b64 vcc, exec, s[8:9]
	s_cbranch_vccnz .LBB0_1897
	v_add_f32_e32 v41, v41, v229
.LBB0_1897:
	s_and_b64 vcc, exec, s[8:9]
	s_cbranch_vccnz .LBB0_1899
	v_add_f32_e32 v42, v42, v230
.LBB0_1899:
	s_and_b64 vcc, exec, s[8:9]
	s_cbranch_vccnz .LBB0_1901
	v_add_f32_e32 v43, v43, v231
.LBB0_1901:
	v_mul_f32_e32 v48, 0x3d372713, v42
	v_mul_f32_e32 v48, v42, v48
	v_fma_f32 v48, v42, v48, v42
	v_mul_f32_e32 v48, 0x3fcc422a, v48
	v_mul_f32_e32 v48, 0xbfb8aa3b, v48
	v_exp_f32_e32 v48, v48
	v_mul_f32_e32 v49, 0x3d372713, v41
	v_mul_f32_e32 v49, v41, v49
	v_fma_f32 v49, v41, v49, v41
	v_add_f32_e32 v48, 1.0, v48
	v_mul_f32_e32 v49, 0x3fcc422a, v49
	v_rcp_f32_e32 v48, v48
	v_mul_f32_e32 v49, 0xbfb8aa3b, v49
	v_exp_f32_e32 v49, v49
	v_mul_f32_e32 v50, 0x3d372713, v40
	v_mul_f32_e32 v50, v40, v50
	v_fma_f32 v50, v40, v50, v40
	v_mul_f32_e32 v48, v42, v48
	v_mul_f32_e32 v42, 0x3d372713, v47
	v_mul_f32_e32 v50, 0x3fcc422a, v50
	v_mul_f32_e32 v42, v47, v42
	v_add_f32_e32 v49, 1.0, v49
	v_mul_f32_e32 v50, 0xbfb8aa3b, v50
	v_fma_f32 v42, v47, v42, v47
	v_rcp_f32_e32 v49, v49
	v_exp_f32_e32 v50, v50
	v_mul_f32_e32 v42, 0x3fcc422a, v42
	v_mul_f32_e32 v42, 0xbfb8aa3b, v42
	v_exp_f32_e32 v42, v42
	v_mul_f32_e32 v49, v41, v49
	v_add_f32_e32 v41, 1.0, v50
	v_rcp_f32_e32 v41, v41
	v_add_f32_e32 v42, 1.0, v42
	v_mul_f32_e32 v51, 0x3d372713, v45
	v_rcp_f32_e32 v42, v42
	v_mul_f32_e32 v51, v45, v51
	v_fma_f32 v51, v45, v51, v45
	v_mul_f32_e32 v51, 0x3fcc422a, v51
	v_mul_f32_e32 v52, v40, v41
	v_mul_f32_e32 v41, 0x3d372713, v44
	v_mul_f32_e32 v50, 0x3d372713, v46
	v_mul_f32_e32 v51, 0xbfb8aa3b, v51
	v_mul_f32_e32 v41, v44, v41
	v_mul_f32_e32 v50, v46, v50
	v_exp_f32_e32 v51, v51
	v_mul_f32_e32 v47, v47, v42
	v_fma_f32 v41, v44, v41, v44
	v_mul_f32_e32 v42, 0x3d372713, v43
	v_fma_f32 v50, v46, v50, v46
	v_mul_f32_e32 v41, 0x3fcc422a, v41
	v_mul_f32_e32 v42, v43, v42
	v_mul_f32_e32 v50, 0x3fcc422a, v50
	v_mul_f32_e32 v41, 0xbfb8aa3b, v41
	v_fma_f32 v42, v43, v42, v43
	v_mul_f32_e32 v50, 0xbfb8aa3b, v50
	v_exp_f32_e32 v41, v41
	v_mul_f32_e32 v42, 0x3fcc422a, v42
	v_exp_f32_e32 v50, v50
	v_add_f32_e32 v40, 1.0, v51
	v_mul_f32_e32 v42, 0xbfb8aa3b, v42
	v_rcp_f32_e32 v40, v40
	v_exp_f32_e32 v42, v42
	v_add_f32_e32 v41, 1.0, v41
	v_add_f32_e32 v50, 1.0, v50
	v_rcp_f32_e32 v41, v41
	v_rcp_f32_e32 v50, v50
	v_mul_f32_e32 v45, v45, v40
	v_add_f32_e32 v40, 1.0, v42
	v_rcp_f32_e32 v42, v40
	v_mul_f32_e32 v44, v44, v41
	v_lshlrev_b64 v[40:41], 9, v[124:125]
	v_mul_f32_e32 v46, v46, v50
	v_lshl_add_u64 v[40:41], v[136:137], 0, v[40:41]
	v_mul_f32_e32 v50, v43, v42
	v_cvt_pk_bf16_f32 v42, v44, v45
	v_cvt_pk_bf16_f32 v43, v46, v47
	v_add_co_u32_e32 v46, vcc, 0x12000, v40
	v_cvt_pk_bf16_f32 v44, v52, v49
	v_cvt_pk_bf16_f32 v45, v48, v50
	s_nop 1
	v_addc_co_u32_e32 v47, vcc, 0, v41, vcc
	s_and_b64 vcc, exec, s[8:9]
	global_store_dwordx4 v[46:47], v[42:45], off
	s_cbranch_vccnz .LBB0_1903
	s_nop 0
	v_add_f32_e32 v36, v36, v232
; __device__ __forceinline__ unsigned cvt_pk_bf16(float lo, float hi) { unsigned r; asm volatile("v_cvt_pk_bf16_f32 %0, %1, %2" : "=v"(r) : "v"(lo), "v"(hi)); return r; }
; __device__ __forceinline__ float fsigmoid(float x) { return __builtin_amdgcn_rcpf(1.0f + __builtin_amdgcn_exp2f(-1.4426950408889634f * x)); }
;     __device__ __forceinline__ void operator()(const f32x4 (&acc)[2][2][4][2], const Unit& u, int wr, int wc, int fr, int fq) const {
;     ...
;                     for (int n = 0; n < 2; ++n)
; #pragma unroll
;                         for (int e = 0; e < 4; ++e) {
;                             float x = acc[ai][bj][m][n][e] * rs;
;                             if (cbias) x += cbias[(u.pm >> 5) * 256 + (col0 - colt) + bj * HALF + n * 4 + e];
;                             if (act == 1) x = fsigmoid(x);
;                             else if (act == 2) { const float z = 1.5957691216057308f * (x + 0.044715f * x * x * x); x = x * fsigmoid(z); }
;                             h[n * 4 + e] = x;
;                         }
;                     u32x4 w; w.x = cvt_pk_bf16(h[0], h[1]); w.y = cvt_pk_bf16(h[2], h[3]); w.z = cvt_pk_bf16(h[4], h[5]); w.w = cvt_pk_bf16(h[6], h[7]);
;                     *(u32x4*)(rowp + bj * HALF) = w;
.LBB0_1903:
	s_and_b64 vcc, exec, s[8:9]
	s_cbranch_vccnz .LBB0_1905
	v_add_f32_e32 v37, v37, v233
.LBB0_1905:
	s_and_b64 vcc, exec, s[8:9]
	s_cbranch_vccnz .LBB0_1907
	v_add_f32_e32 v38, v38, v234
.LBB0_1907:
	s_and_b64 vcc, exec, s[8:9]
	s_cbranch_vccnz .LBB0_1909
	v_add_f32_e32 v39, v39, v235
.LBB0_1909:
	s_and_b64 vcc, exec, s[8:9]
	s_cbranch_vccnz .LBB0_1911
	v_add_f32_e32 v32, v32, v236
.LBB0_1911:
	s_and_b64 vcc, exec, s[8:9]
	s_cbranch_vccnz .LBB0_1913
	v_add_f32_e32 v33, v33, v237
.LBB0_1913:
	s_and_b64 vcc, exec, s[8:9]
	s_cbranch_vccnz .LBB0_1915
	v_add_f32_e32 v34, v34, v238
.LBB0_1915:
	s_and_b64 vcc, exec, s[8:9]
	s_cbranch_vccnz .LBB0_1917
	v_add_f32_e32 v35, v35, v239
.LBB0_1917:
	v_mul_f32_e32 v42, 0x3d372713, v34
	v_mul_f32_e32 v43, 0x3d372713, v33
	v_mul_f32_e32 v44, 0x3d372713, v32
	v_mul_f32_e32 v42, v34, v42
	v_mul_f32_e32 v43, v33, v43
	v_mul_f32_e32 v44, v32, v44
	v_fma_f32 v42, v34, v42, v34
	v_fma_f32 v43, v33, v43, v33
	v_fma_f32 v44, v32, v44, v32
	v_mul_f32_e32 v42, 0x3fcc422a, v42
	v_mul_f32_e32 v43, 0x3fcc422a, v43
	v_mul_f32_e32 v44, 0x3fcc422a, v44
	v_mul_f32_e32 v42, 0xbfb8aa3b, v42
	v_mul_f32_e32 v43, 0xbfb8aa3b, v43
	v_mul_f32_e32 v44, 0xbfb8aa3b, v44
	v_exp_f32_e32 v42, v42
	v_exp_f32_e32 v43, v43
	v_exp_f32_e32 v44, v44
	v_mul_f32_e32 v45, 0x3d372713, v39
	v_add_f32_e32 v42, 1.0, v42
	v_add_f32_e32 v43, 1.0, v43
	v_add_f32_e32 v44, 1.0, v44
	v_rcp_f32_e32 v42, v42
	v_rcp_f32_e32 v43, v43
	v_rcp_f32_e32 v44, v44
	v_mul_f32_e32 v45, v39, v45
	v_fma_f32 v45, v39, v45, v39
	v_mul_f32_e32 v45, 0x3fcc422a, v45
	v_mul_f32_e32 v45, 0xbfb8aa3b, v45
	v_exp_f32_e32 v45, v45
	v_mul_f32_e32 v42, v34, v42
	v_mul_f32_e32 v34, v33, v43
	v_mul_f32_e32 v43, v32, v44
	v_mul_f32_e32 v33, 0x3d372713, v38
	v_mul_f32_e32 v44, 0x3d372713, v37
	v_mul_f32_e32 v33, v38, v33
	v_mul_f32_e32 v44, v37, v44
	v_fma_f32 v33, v38, v33, v38
	v_fma_f32 v44, v37, v44, v37
	v_mul_f32_e32 v33, 0x3fcc422a, v33
	v_mul_f32_e32 v44, 0x3fcc422a, v44
	v_add_f32_e32 v32, 1.0, v45
	v_mul_f32_e32 v33, 0xbfb8aa3b, v33
	v_mul_f32_e32 v44, 0xbfb8aa3b, v44
	v_rcp_f32_e32 v32, v32
	v_exp_f32_e32 v33, v33
	v_exp_f32_e32 v44, v44
	v_mul_f32_e32 v45, 0x3d372713, v35
	v_mul_f32_e32 v39, v39, v32
	v_add_f32_e32 v32, 1.0, v33
	v_add_f32_e32 v33, 1.0, v44
	v_mul_f32_e32 v44, 0x3d372713, v36
	v_mul_f32_e32 v44, v36, v44
	v_mul_f32_e32 v45, v35, v45
	v_fma_f32 v44, v36, v44, v36
	v_fma_f32 v45, v35, v45, v35
	v_mul_f32_e32 v44, 0x3fcc422a, v44
	v_mul_f32_e32 v45, 0x3fcc422a, v45
	v_mul_f32_e32 v44, 0xbfb8aa3b, v44
	v_mul_f32_e32 v45, 0xbfb8aa3b, v45
	v_exp_f32_e32 v44, v44
	v_exp_f32_e32 v45, v45
	v_rcp_f32_e32 v32, v32
	v_rcp_f32_e32 v33, v33
	v_add_f32_e32 v44, 1.0, v44
	v_add_f32_e32 v45, 1.0, v45
	v_rcp_f32_e32 v44, v44
	v_rcp_f32_e32 v45, v45
	s_mov_b64 s[36:37], 0x12000
	v_lshl_add_u64 v[40:41], v[40:41], 0, s[36:37]
	v_mul_f32_e32 v38, v38, v32
	v_mul_f32_e32 v32, v37, v33
	v_mul_f32_e32 v33, v36, v44
	v_mul_f32_e32 v35, v35, v45
	s_and_b64 vcc, exec, s[8:9]
	v_cvt_pk_bf16_f32 v32, v33, v32
	v_cvt_pk_bf16_f32 v33, v38, v39
	v_cvt_pk_bf16_f32 v34, v43, v34
	v_cvt_pk_bf16_f32 v35, v42, v35
	global_store_dwordx4 v[40:41], v[32:35], off offset:256
	s_cbranch_vccnz .LBB0_1919
	s_nop 0
	v_add_f32_e32 v28, v28, v224
.LBB0_1919:
	s_and_b64 vcc, exec, s[8:9]
	s_cbranch_vccnz .LBB0_1921
	v_add_f32_e32 v29, v29, v225
.LBB0_1921:
	s_and_b64 vcc, exec, s[8:9]
	s_cbranch_vccnz .LBB0_1923
	v_add_f32_e32 v30, v30, v226
.LBB0_1923:
	s_and_b64 vcc, exec, s[8:9]
	s_cbranch_vccnz .LBB0_1925
	v_add_f32_e32 v31, v31, v227
.LBB0_1925:
	s_and_b64 vcc, exec, s[8:9]
	s_cbranch_vccnz .LBB0_1927
	v_add_f32_e32 v24, v24, v228
.LBB0_1927:
	s_and_b64 vcc, exec, s[8:9]
	s_cbranch_vccnz .LBB0_1929
	v_add_f32_e32 v25, v25, v229
.LBB0_1929:
	s_and_b64 vcc, exec, s[8:9]
	s_cbranch_vccnz .LBB0_1931
	v_add_f32_e32 v26, v26, v230
.LBB0_1931:
	s_and_b64 vcc, exec, s[8:9]
	s_cbranch_vccnz .LBB0_1933
	v_add_f32_e32 v27, v27, v231
.LBB0_1933:
	v_mul_f32_e32 v32, 0x3d372713, v26
	v_mul_f32_e32 v32, v26, v32
	v_fma_f32 v32, v26, v32, v26
	v_mul_f32_e32 v32, 0x3fcc422a, v32
	v_mul_f32_e32 v32, 0xbfb8aa3b, v32
	v_exp_f32_e32 v32, v32
	v_mul_f32_e32 v33, 0x3d372713, v25
	v_mul_f32_e32 v33, v25, v33
	v_fma_f32 v33, v25, v33, v25
	v_add_f32_e32 v32, 1.0, v32
	v_mul_f32_e32 v33, 0x3fcc422a, v33
	v_rcp_f32_e32 v32, v32
	v_mul_f32_e32 v33, 0xbfb8aa3b, v33
	v_exp_f32_e32 v33, v33
	v_mul_f32_e32 v34, 0x3d372713, v24
	v_mul_f32_e32 v34, v24, v34
	v_fma_f32 v34, v24, v34, v24
	v_mul_f32_e32 v32, v26, v32
	v_mul_f32_e32 v26, 0x3d372713, v31
	v_mul_f32_e32 v34, 0x3fcc422a, v34
	v_mul_f32_e32 v26, v31, v26
	v_add_f32_e32 v33, 1.0, v33
	v_mul_f32_e32 v34, 0xbfb8aa3b, v34
	v_fma_f32 v26, v31, v26, v31
	v_rcp_f32_e32 v33, v33
	v_exp_f32_e32 v34, v34
	v_mul_f32_e32 v26, 0x3fcc422a, v26
	v_mul_f32_e32 v26, 0xbfb8aa3b, v26
	v_exp_f32_e32 v26, v26
	v_mul_f32_e32 v33, v25, v33
	v_add_f32_e32 v25, 1.0, v34
	v_rcp_f32_e32 v25, v25
	v_add_f32_e32 v26, 1.0, v26
	v_mul_f32_e32 v35, 0x3d372713, v29
	v_rcp_f32_e32 v26, v26
	v_mul_f32_e32 v35, v29, v35
	v_fma_f32 v35, v29, v35, v29
	v_mul_f32_e32 v35, 0x3fcc422a, v35
	v_mul_f32_e32 v36, v24, v25
	v_mul_f32_e32 v25, 0x3d372713, v28
	v_mul_f32_e32 v34, 0x3d372713, v30
	v_mul_f32_e32 v35, 0xbfb8aa3b, v35
	v_mul_f32_e32 v25, v28, v25
	v_mul_f32_e32 v34, v30, v34
	v_exp_f32_e32 v35, v35
	v_mul_f32_e32 v31, v31, v26
	v_fma_f32 v25, v28, v25, v28
	v_mul_f32_e32 v26, 0x3d372713, v27
	v_fma_f32 v34, v30, v34, v30
	v_mul_f32_e32 v25, 0x3fcc422a, v25
	v_mul_f32_e32 v26, v27, v26
	v_mul_f32_e32 v34, 0x3fcc422a, v34
	v_mul_f32_e32 v25, 0xbfb8aa3b, v25
	v_fma_f32 v26, v27, v26, v27
	v_mul_f32_e32 v34, 0xbfb8aa3b, v34
	v_exp_f32_e32 v25, v25
	v_mul_f32_e32 v26, 0x3fcc422a, v26
	v_exp_f32_e32 v34, v34
	v_add_f32_e32 v24, 1.0, v35
	v_mul_f32_e32 v26, 0xbfb8aa3b, v26
	v_rcp_f32_e32 v24, v24
	v_exp_f32_e32 v26, v26
	v_add_f32_e32 v25, 1.0, v25
	v_add_f32_e32 v34, 1.0, v34
	v_rcp_f32_e32 v25, v25
	v_rcp_f32_e32 v34, v34
	v_mul_f32_e32 v29, v29, v24
	v_add_f32_e32 v24, 1.0, v26
	v_rcp_f32_e32 v26, v24
	v_mul_f32_e32 v28, v28, v25
	v_lshlrev_b64 v[24:25], 9, v[124:125]
	v_mul_f32_e32 v30, v30, v34
	v_lshl_add_u64 v[24:25], v[136:137], 0, v[24:25]
	v_mul_f32_e32 v34, v27, v26
	v_cvt_pk_bf16_f32 v26, v28, v29
	v_cvt_pk_bf16_f32 v27, v30, v31
	v_add_co_u32_e32 v30, vcc, 0x14000, v24
	v_cvt_pk_bf16_f32 v28, v36, v33
	v_cvt_pk_bf16_f32 v29, v32, v34
	s_nop 1
	v_addc_co_u32_e32 v31, vcc, 0, v25, vcc
	s_and_b64 vcc, exec, s[8:9]
	global_store_dwordx4 v[30:31], v[26:29], off
	s_cbranch_vccnz .LBB0_1935
	s_nop 0
	v_add_f32_e32 v20, v20, v232
; __device__ __forceinline__ unsigned cvt_pk_bf16(float lo, float hi) { unsigned r; asm volatile("v_cvt_pk_bf16_f32 %0, %1, %2" : "=v"(r) : "v"(lo), "v"(hi)); return r; }
; __device__ __forceinline__ float fsigmoid(float x) { return __builtin_amdgcn_rcpf(1.0f + __builtin_amdgcn_exp2f(-1.4426950408889634f * x)); }
;     __device__ __forceinline__ void operator()(const f32x4 (&acc)[2][2][4][2], const Unit& u, int wr, int wc, int fr, int fq) const {
;     ...
;                     for (int n = 0; n < 2; ++n)
; #pragma unroll
;                         for (int e = 0; e < 4; ++e) {
;                             float x = acc[ai][bj][m][n][e] * rs;
;                             if (cbias) x += cbias[(u.pm >> 5) * 256 + (col0 - colt) + bj * HALF + n * 4 + e];
;                             if (act == 1) x = fsigmoid(x);
;                             else if (act == 2) { const float z = 1.5957691216057308f * (x + 0.044715f * x * x * x); x = x * fsigmoid(z); }
;                             h[n * 4 + e] = x;
;                         }
;                     u32x4 w; w.x = cvt_pk_bf16(h[0], h[1]); w.y = cvt_pk_bf16(h[2], h[3]); w.z = cvt_pk_bf16(h[4], h[5]); w.w = cvt_pk_bf16(h[6], h[7]);
;                     *(u32x4*)(rowp + bj * HALF) = w;
.LBB0_1935:
	s_and_b64 vcc, exec, s[8:9]
	s_cbranch_vccnz .LBB0_1937
	v_add_f32_e32 v21, v21, v233
.LBB0_1937:
	s_and_b64 vcc, exec, s[8:9]
	s_cbranch_vccnz .LBB0_1939
	v_add_f32_e32 v22, v22, v234
.LBB0_1939:
	s_and_b64 vcc, exec, s[8:9]
	s_cbranch_vccnz .LBB0_1941
	v_add_f32_e32 v23, v23, v235
.LBB0_1941:
	s_and_b64 vcc, exec, s[8:9]
	s_cbranch_vccnz .LBB0_1943
	v_add_f32_e32 v16, v16, v236
.LBB0_1943:
	s_and_b64 vcc, exec, s[8:9]
	s_cbranch_vccnz .LBB0_1945
	v_add_f32_e32 v17, v17, v237
.LBB0_1945:
	s_and_b64 vcc, exec, s[8:9]
	s_cbranch_vccnz .LBB0_1947
	v_add_f32_e32 v18, v18, v238
.LBB0_1947:
	s_and_b64 vcc, exec, s[8:9]
	s_cbranch_vccnz .LBB0_1949
	v_add_f32_e32 v19, v19, v239
.LBB0_1949:
	v_mul_f32_e32 v26, 0x3d372713, v18
	v_mul_f32_e32 v27, 0x3d372713, v17
	v_mul_f32_e32 v28, 0x3d372713, v16
	v_mul_f32_e32 v26, v18, v26
	v_mul_f32_e32 v27, v17, v27
	v_mul_f32_e32 v28, v16, v28
	v_fma_f32 v26, v18, v26, v18
	v_fma_f32 v27, v17, v27, v17
	v_fma_f32 v28, v16, v28, v16
	v_mul_f32_e32 v26, 0x3fcc422a, v26
	v_mul_f32_e32 v27, 0x3fcc422a, v27
	v_mul_f32_e32 v28, 0x3fcc422a, v28
	v_mul_f32_e32 v26, 0xbfb8aa3b, v26
	v_mul_f32_e32 v27, 0xbfb8aa3b, v27
	v_mul_f32_e32 v28, 0xbfb8aa3b, v28
	v_exp_f32_e32 v26, v26
	v_exp_f32_e32 v27, v27
	v_exp_f32_e32 v28, v28
	v_mul_f32_e32 v29, 0x3d372713, v23
	v_add_f32_e32 v26, 1.0, v26
	v_add_f32_e32 v27, 1.0, v27
	v_add_f32_e32 v28, 1.0, v28
	v_rcp_f32_e32 v26, v26
	v_rcp_f32_e32 v27, v27
	v_rcp_f32_e32 v28, v28
	v_mul_f32_e32 v29, v23, v29
	v_fma_f32 v29, v23, v29, v23
	v_mul_f32_e32 v29, 0x3fcc422a, v29
	v_mul_f32_e32 v29, 0xbfb8aa3b, v29
	v_exp_f32_e32 v29, v29
	v_mul_f32_e32 v26, v18, v26
	v_mul_f32_e32 v18, v17, v27
	v_mul_f32_e32 v27, v16, v28
	v_mul_f32_e32 v17, 0x3d372713, v22
	v_mul_f32_e32 v28, 0x3d372713, v21
	v_mul_f32_e32 v17, v22, v17
	v_mul_f32_e32 v28, v21, v28
	v_fma_f32 v17, v22, v17, v22
	v_fma_f32 v28, v21, v28, v21
	v_mul_f32_e32 v17, 0x3fcc422a, v17
	v_mul_f32_e32 v28, 0x3fcc422a, v28
	v_add_f32_e32 v16, 1.0, v29
	v_mul_f32_e32 v17, 0xbfb8aa3b, v17
	v_mul_f32_e32 v28, 0xbfb8aa3b, v28
	v_rcp_f32_e32 v16, v16
	v_exp_f32_e32 v17, v17
	v_exp_f32_e32 v28, v28
	v_mul_f32_e32 v29, 0x3d372713, v19
	v_mul_f32_e32 v23, v23, v16
	v_add_f32_e32 v16, 1.0, v17
	v_add_f32_e32 v17, 1.0, v28
	v_mul_f32_e32 v28, 0x3d372713, v20
	v_mul_f32_e32 v28, v20, v28
	v_mul_f32_e32 v29, v19, v29
	v_fma_f32 v28, v20, v28, v20
	v_fma_f32 v29, v19, v29, v19
	v_mul_f32_e32 v28, 0x3fcc422a, v28
	v_mul_f32_e32 v29, 0x3fcc422a, v29
	v_mul_f32_e32 v28, 0xbfb8aa3b, v28
	v_mul_f32_e32 v29, 0xbfb8aa3b, v29
	v_exp_f32_e32 v28, v28
	v_exp_f32_e32 v29, v29
	v_rcp_f32_e32 v16, v16
	v_rcp_f32_e32 v17, v17
	v_add_f32_e32 v28, 1.0, v28
	v_add_f32_e32 v29, 1.0, v29
	v_rcp_f32_e32 v28, v28
	v_rcp_f32_e32 v29, v29
	s_mov_b64 s[36:37], 0x14000
	v_lshl_add_u64 v[24:25], v[24:25], 0, s[36:37]
	v_mul_f32_e32 v22, v22, v16
	v_mul_f32_e32 v16, v21, v17
	v_mul_f32_e32 v17, v20, v28
	v_mul_f32_e32 v19, v19, v29
	s_and_b64 vcc, exec, s[8:9]
	v_cvt_pk_bf16_f32 v16, v17, v16
	v_cvt_pk_bf16_f32 v17, v22, v23
	v_cvt_pk_bf16_f32 v18, v27, v18
	v_cvt_pk_bf16_f32 v19, v26, v19
	global_store_dwordx4 v[24:25], v[16:19], off offset:256
	s_cbranch_vccnz .LBB0_1951
	s_nop 0
	v_add_f32_e32 v12, v12, v224
.LBB0_1951:
	s_and_b64 vcc, exec, s[8:9]
	s_cbranch_vccnz .LBB0_1953
	v_add_f32_e32 v13, v13, v225
.LBB0_1953:
	s_and_b64 vcc, exec, s[8:9]
	s_cbranch_vccnz .LBB0_1955
	v_add_f32_e32 v14, v14, v226
.LBB0_1955:
	s_and_b64 vcc, exec, s[8:9]
	s_cbranch_vccnz .LBB0_1957
	v_add_f32_e32 v15, v15, v227
.LBB0_1957:
	s_and_b64 vcc, exec, s[8:9]
	s_cbranch_vccnz .LBB0_1959
	v_add_f32_e32 v8, v8, v228
; __device__ __forceinline__ unsigned cvt_pk_bf16(float lo, float hi) { unsigned r; asm volatile("v_cvt_pk_bf16_f32 %0, %1, %2" : "=v"(r) : "v"(lo), "v"(hi)); return r; }
; __device__ __forceinline__ float fsigmoid(float x) { return __builtin_amdgcn_rcpf(1.0f + __builtin_amdgcn_exp2f(-1.4426950408889634f * x)); }
;     __device__ __forceinline__ void operator()(const f32x4 (&acc)[2][2][4][2], const Unit& u, int wr, int wc, int fr, int fq) const {
;     ...
;                     for (int n = 0; n < 2; ++n)
; #pragma unroll
;                         for (int e = 0; e < 4; ++e) {
;                             float x = acc[ai][bj][m][n][e] * rs;
;                             if (cbias) x += cbias[(u.pm >> 5) * 256 + (col0 - colt) + bj * HALF + n * 4 + e];
;                             if (act == 1) x = fsigmoid(x);
;                             else if (act == 2) { const float z = 1.5957691216057308f * (x + 0.044715f * x * x * x); x = x * fsigmoid(z); }
;                             h[n * 4 + e] = x;
;                         }
;                     u32x4 w; w.x = cvt_pk_bf16(h[0], h[1]); w.y = cvt_pk_bf16(h[2], h[3]); w.z = cvt_pk_bf16(h[4], h[5]); w.w = cvt_pk_bf16(h[6], h[7]);
;                     *(u32x4*)(rowp + bj * HALF) = w;
.LBB0_1959:
	s_and_b64 vcc, exec, s[8:9]
	s_cbranch_vccnz .LBB0_1961
	v_add_f32_e32 v9, v9, v229
.LBB0_1961:
	s_and_b64 vcc, exec, s[8:9]
	s_cbranch_vccnz .LBB0_1963
	v_add_f32_e32 v10, v10, v230
.LBB0_1963:
	s_and_b64 vcc, exec, s[8:9]
	s_cbranch_vccnz .LBB0_1965
	v_add_f32_e32 v11, v11, v231
.LBB0_1965:
	v_mul_f32_e32 v16, 0x3d372713, v10
	v_mul_f32_e32 v16, v10, v16
	v_fma_f32 v16, v10, v16, v10
	v_mul_f32_e32 v16, 0x3fcc422a, v16
	v_mul_f32_e32 v16, 0xbfb8aa3b, v16
	v_exp_f32_e32 v16, v16
	v_mul_f32_e32 v17, 0x3d372713, v9
	v_mul_f32_e32 v17, v9, v17
	v_fma_f32 v17, v9, v17, v9
	v_add_f32_e32 v16, 1.0, v16
	v_mul_f32_e32 v17, 0x3fcc422a, v17
	v_rcp_f32_e32 v16, v16
	v_mul_f32_e32 v17, 0xbfb8aa3b, v17
	v_exp_f32_e32 v17, v17
	v_mul_f32_e32 v18, 0x3d372713, v8
	v_mul_f32_e32 v18, v8, v18
	v_fma_f32 v18, v8, v18, v8
	v_mul_f32_e32 v16, v10, v16
	v_mul_f32_e32 v10, 0x3d372713, v15
	v_mul_f32_e32 v18, 0x3fcc422a, v18
	v_mul_f32_e32 v10, v15, v10
	v_add_f32_e32 v17, 1.0, v17
	v_mul_f32_e32 v18, 0xbfb8aa3b, v18
	v_fma_f32 v10, v15, v10, v15
	v_rcp_f32_e32 v17, v17
	v_exp_f32_e32 v18, v18
	v_mul_f32_e32 v10, 0x3fcc422a, v10
	v_mul_f32_e32 v10, 0xbfb8aa3b, v10
	v_exp_f32_e32 v10, v10
	v_mul_f32_e32 v17, v9, v17
	v_add_f32_e32 v9, 1.0, v18
	v_rcp_f32_e32 v9, v9
	v_add_f32_e32 v10, 1.0, v10
	v_mul_f32_e32 v19, 0x3d372713, v13
	v_rcp_f32_e32 v10, v10
	v_mul_f32_e32 v19, v13, v19
	v_fma_f32 v19, v13, v19, v13
	v_mul_f32_e32 v19, 0x3fcc422a, v19
	v_mul_f32_e32 v20, v8, v9
	v_mul_f32_e32 v9, 0x3d372713, v12
	v_mul_f32_e32 v18, 0x3d372713, v14
	v_mul_f32_e32 v19, 0xbfb8aa3b, v19
	v_mul_f32_e32 v9, v12, v9
	v_mul_f32_e32 v18, v14, v18
	v_exp_f32_e32 v19, v19
	v_mul_f32_e32 v15, v15, v10
	v_fma_f32 v9, v12, v9, v12
	v_mul_f32_e32 v10, 0x3d372713, v11
	v_fma_f32 v18, v14, v18, v14
	v_mul_f32_e32 v9, 0x3fcc422a, v9
	v_mul_f32_e32 v10, v11, v10
	v_mul_f32_e32 v18, 0x3fcc422a, v18
	v_mul_f32_e32 v9, 0xbfb8aa3b, v9
	v_fma_f32 v10, v11, v10, v11
	v_mul_f32_e32 v18, 0xbfb8aa3b, v18
	v_exp_f32_e32 v9, v9
	v_mul_f32_e32 v10, 0x3fcc422a, v10
	v_exp_f32_e32 v18, v18
	v_add_f32_e32 v8, 1.0, v19
	v_mul_f32_e32 v10, 0xbfb8aa3b, v10
	v_rcp_f32_e32 v8, v8
	v_exp_f32_e32 v10, v10
	v_add_f32_e32 v9, 1.0, v9
	v_add_f32_e32 v18, 1.0, v18
	v_rcp_f32_e32 v9, v9
	v_rcp_f32_e32 v18, v18
	v_mul_f32_e32 v13, v13, v8
	v_add_f32_e32 v8, 1.0, v10
	v_rcp_f32_e32 v10, v8
	v_mul_f32_e32 v12, v12, v9
	v_lshlrev_b64 v[8:9], 9, v[124:125]
	v_mul_f32_e32 v14, v14, v18
	v_lshl_add_u64 v[8:9], v[136:137], 0, v[8:9]
	v_mul_f32_e32 v18, v11, v10
	v_cvt_pk_bf16_f32 v10, v12, v13
	v_cvt_pk_bf16_f32 v11, v14, v15
	v_add_co_u32_e32 v14, vcc, 0x16000, v8
	v_cvt_pk_bf16_f32 v12, v20, v17
	v_cvt_pk_bf16_f32 v13, v16, v18
	s_nop 1
	v_addc_co_u32_e32 v15, vcc, 0, v9, vcc
	s_and_b64 vcc, exec, s[8:9]
	global_store_dwordx4 v[14:15], v[10:13], off
	s_cbranch_vccnz .LBB0_1967
	s_nop 0
	v_add_f32_e32 v4, v4, v232
.LBB0_1967:
	s_and_b64 vcc, exec, s[8:9]
	s_cbranch_vccnz .LBB0_1969
	v_add_f32_e32 v5, v5, v233
.LBB0_1969:
	s_and_b64 vcc, exec, s[8:9]
	s_cbranch_vccnz .LBB0_1971
	v_add_f32_e32 v6, v6, v234
.LBB0_1971:
	s_and_b64 vcc, exec, s[8:9]
	s_cbranch_vccnz .LBB0_1973
	v_add_f32_e32 v7, v7, v235
.LBB0_1973:
	s_and_b64 vcc, exec, s[8:9]
	s_cbranch_vccnz .LBB0_1975
	v_add_f32_e32 v0, v0, v236
.LBB0_1975:
	s_and_b64 vcc, exec, s[8:9]
	s_cbranch_vccnz .LBB0_1977
	v_add_f32_e32 v1, v1, v237
.LBB0_1977:
	s_and_b64 vcc, exec, s[8:9]
	s_cbranch_vccnz .LBB0_1979
	v_add_f32_e32 v2, v2, v238
.LBB0_1979:
	s_and_b64 vcc, exec, s[8:9]
	s_cbranch_vccnz .LBB0_1981
	v_add_f32_e32 v3, v3, v239
